# MLA attention reads rope keys from head-0 copy; removed 7/8 replicated rope-key stores in mla_in epilogue
# speedup vs baseline: 1.0254x; 1.0254x over previous
.LBB0_354:
	s_cmpk_gt_i32 s22, 0xff
	s_mov_b64 s[4:5], -1
	s_cbranch_scc0 .LBB0_370
	s_add_i32 s4, s22, 0xffffff00
	s_lshl_b32 s5, s22, 5
	s_lshr_b32 s4, s4, 3
	s_and_b32 s5, s5, 0xe0
	s_add_i32 s30, s4, s5
	s_lshr_b32 s31, s30, 4
	s_bfe_u32 s23, s22, 0x30004
	s_lshl_b32 s4, s31, 3
	s_or_b32 s36, s4, s23
	s_mul_i32 s4, s36, 0x18000
	s_mul_hi_u32 s5, s36, 0x18000
	s_add_u32 s4, s10, s4
	s_addc_u32 s5, s11, s5
	s_lshl_b64 s[6:7], s[36:37], 16
	s_add_u32 s6, s12, s6
	s_addc_u32 s7, s13, s7
	s_lshl_b32 s30, s30, 7
	s_lshl_b32 s31, s31, 8
	s_and_b32 s30, s30, 0x80
	v_mov_b32_e32 v60, v188
	s_or_b32 s30, s31, s30
	s_movk_i32 s36, 0xc00
	v_and_b32_e32 v64, 15, v60
	v_ashrrev_i32_e32 v0, 1, v60
	v_or_b32_e32 v1, s30, v64
	s_mul_i32 s30, s23, 0x180
	v_bfe_u32 v65, v60, 4, 2
	v_and_b32_e32 v0, 0xffffffe0, v0
	s_add_u32 s30, s8, s30
	v_add_u32_e32 v150, v1, v0
	s_addc_u32 s31, s9, 0
	v_lshlrev_b32_e32 v176, 4, v65
	v_lshl_add_u64 v[8:9], s[30:31], 0, v[176:177]
	v_or_b32_e32 v148, 16, v150
	v_mad_i64_i32 v[0:1], s[30:31], v150, s36, v[8:9]
	v_mad_i64_i32 v[8:9], s[30:31], v148, s36, v[8:9]
	s_mov_b32 s36, 0x2aaaaaab
	v_mul_hi_i32 v48, v60, s36
	v_lshrrev_b32_e32 v49, 31, v48
	v_ashrrev_i32_e32 v48, 2, v48
	v_add_u32_e32 v161, v48, v49
	v_mul_lo_u32 v48, v161, 24
	v_add_u32_e32 v66, 0x100, v60
	v_add_u32_e32 v56, 0x200, v60
	v_sub_u32_e32 v82, v60, v48
	v_mul_hi_i32 v52, v66, s36
	v_mul_hi_i32 v57, v56, s36
	v_lshlrev_b32_e32 v152, 3, v82
	v_lshrrev_b32_e32 v53, 31, v52
	v_ashrrev_i32_e32 v52, 2, v52
	v_lshrrev_b32_e32 v58, 31, v57
	v_ashrrev_i32_e32 v57, 2, v57
	v_mov_b64_e32 v[70:71], s[4:5]
	v_ashrrev_i32_e32 v153, 31, v152
	v_add_u32_e32 v174, v52, v53
	v_add_u32_e32 v175, v57, v58
	v_ashrrev_i32_e32 v61, 31, v60
	v_mad_i64_i32 v[48:49], s[30:31], v161, s18, v[70:71]
	v_lshlrev_b64 v[72:73], 1, v[152:153]
	s_mul_i32 m0, s23, 0x18000
	v_cmp_le_u32_e32 vcc, 0x80, v152
	v_mov_b32_e32 v73, m0
	s_nop 1
	v_cndmask_b32_e32 v73, 0, v73, vcc
	v_sub_u32_e32 v72, v72, v73
	v_ashrrev_i32_e32 v73, 31, v72
	v_mul_lo_u32 v52, v174, 24
	v_mul_lo_u32 v57, v175, 24
	v_lshrrev_b32_e32 v61, 30, v61
	v_ashrrev_i32_e32 v67, 31, v66
	v_lshl_add_u64 v[48:49], v[48:49], 0, v[72:73]
	v_sub_u32_e32 v83, v66, v52
	v_sub_u32_e32 v84, v56, v57
	v_add_u32_e32 v61, v60, v61
	v_lshrrev_b32_e32 v67, 30, v67
	global_load_dwordx4 v[40:43], v[0:1], off
	global_load_dwordx4 v[32:35], v[0:1], off offset:64
	global_load_dwordx4 v[24:27], v[0:1], off offset:128
	global_load_dwordx4 v[16:19], v[0:1], off offset:192
	global_load_dwordx4 v[4:7], v[0:1], off offset:256
	s_nop 0
	global_load_dwordx4 v[0:3], v[0:1], off offset:320
	s_nop 0
	global_load_dwordx4 v[44:47], v[8:9], off
	global_load_dwordx4 v[36:39], v[8:9], off offset:64
	global_load_dwordx4 v[28:31], v[8:9], off offset:128
	global_load_dwordx4 v[20:23], v[8:9], off offset:192
	global_load_dwordx4 v[12:15], v[8:9], off offset:256
	s_nop 0
	global_load_dwordx4 v[8:11], v[8:9], off offset:320
	v_lshlrev_b32_e32 v154, 3, v83
	global_load_dwordx4 v[48:51], v[48:49], off
	v_lshlrev_b32_e32 v156, 3, v84
	v_ashrrev_i32_e32 v78, 2, v61
	v_add_u32_e32 v67, v66, v67
	v_ashrrev_i32_e32 v155, 31, v154
	v_ashrrev_i32_e32 v157, 31, v156
	v_and_b32_e32 v61, -4, v61
	v_ashrrev_i32_e32 v79, 31, v78
	v_ashrrev_i32_e32 v80, 2, v67
	v_and_b32_e32 v67, -4, v67
	v_mad_i64_i32 v[52:53], s[30:31], v174, s18, v[70:71]
	v_lshlrev_b64 v[74:75], 1, v[154:155]
	s_mul_i32 m0, s23, 0x18000
	v_cmp_le_u32_e32 vcc, 0x80, v154
	v_mov_b32_e32 v75, m0
	s_nop 1
	v_cndmask_b32_e32 v75, 0, v75, vcc
	v_sub_u32_e32 v74, v74, v75
	v_ashrrev_i32_e32 v75, 31, v74
	v_mad_i64_i32 v[56:57], s[30:31], v175, s18, v[70:71]
	v_lshlrev_b64 v[76:77], 1, v[156:157]
	s_mul_i32 m0, s23, 0x18000
	v_cmp_le_u32_e32 vcc, 0x80, v156
	v_mov_b32_e32 v77, m0
	s_nop 1
	v_cndmask_b32_e32 v77, 0, v77, vcc
	v_sub_u32_e32 v76, v76, v77
	v_ashrrev_i32_e32 v77, 31, v76
	v_sub_u32_e32 v85, v60, v61
	v_lshlrev_b64 v[60:61], 9, v[78:79]
	v_sub_u32_e32 v79, v66, v67
	v_ashrrev_i32_e32 v81, 31, v80
	v_lshl_add_u64 v[52:53], v[52:53], 0, v[74:75]
	v_lshl_add_u64 v[56:57], v[56:57], 0, v[76:77]
	v_lshlrev_b32_e32 v158, 3, v85
	v_lshlrev_b64 v[66:67], 9, v[80:81]
	v_lshlrev_b32_e32 v164, 3, v79
	global_load_dwordx4 v[52:55], v[52:53], off
	v_lshl_add_u64 v[60:61], s[6:7], 0, v[60:61]
	global_load_dwordx4 v[56:59], v[56:57], off
	v_ashrrev_i32_e32 v159, 31, v158
	v_lshl_add_u64 v[66:67], s[6:7], 0, v[66:67]
	v_ashrrev_i32_e32 v165, 31, v164
	v_lshl_add_u64 v[162:163], v[158:159], 1, v[60:61]
	v_lshl_add_u64 v[166:167], v[164:165], 1, v[66:67]
	global_load_dwordx4 v[60:63], v[162:163], off
	global_load_dwordx4 v[66:69], v[166:167], off
	s_movk_i32 s6, 0xd0
	v_mul_lo_u32 v178, v161, s6
	v_lshlrev_b32_e32 v81, 4, v82
	v_lshl_add_u32 v81, v178, 1, v81
	s_barrier
	v_mul_lo_u32 v179, v174, s6
	v_mul_lo_u32 v180, v175, s6
	v_mul_lo_u32 v181, v78, 40
	v_mul_lo_u32 v182, v80, 40
	v_lshl_add_u64 v[168:169], s[4:5], 0, v[72:73]
	v_lshl_add_u64 v[170:171], s[4:5], 0, v[74:75]
	v_lshl_add_u64 v[172:173], s[4:5], 0, v[76:77]
	v_cmp_lt_i32_e32 vcc, v189, v202
	s_waitcnt vmcnt(4)
	ds_write_b128 v81, v[48:51]
	v_lshlrev_b32_e32 v48, 4, v83
	v_lshl_add_u32 v82, v179, 1, v48
	v_lshlrev_b32_e32 v48, 4, v84
	v_lshl_add_u32 v83, v180, 1, v48
	v_lshlrev_b32_e32 v48, 4, v85
	v_lshl_add_u32 v78, v181, 1, v48
	v_lshlrev_b32_e32 v48, 4, v79
	v_lshl_add_u32 v79, v182, 1, v48
	v_add_u32_e32 v48, 32, v161
	v_mad_i64_i32 v[48:49], s[6:7], v48, s18, v[70:71]
	v_lshl_add_u64 v[48:49], v[48:49], 0, v[72:73]
	global_load_dwordx4 v[48:51], v[48:49], off
	s_waitcnt vmcnt(4)
	ds_write_b128 v82, v[52:55]
	v_add_u32_e32 v52, 32, v174
	s_waitcnt vmcnt(3)
	ds_write_b128 v83, v[56:59]
	v_add_u32_e32 v56, 32, v175
	v_mad_i64_i32 v[52:53], s[6:7], v52, s18, v[70:71]
	v_mad_i64_i32 v[56:57], s[6:7], v56, s18, v[70:71]
	s_waitcnt vmcnt(2)
	ds_write_b128 v78, v[60:63] offset:13312
	s_waitcnt vmcnt(1)
	ds_write_b128 v79, v[66:69] offset:13312
	v_lshl_add_u64 v[52:53], v[52:53], 0, v[74:75]
	v_lshl_add_u64 v[56:57], v[56:57], 0, v[76:77]
	global_load_dwordx4 v[52:55], v[52:53], off
	s_nop 0
	global_load_dwordx4 v[56:59], v[56:57], off
	s_nop 0
	global_load_dwordx4 v[60:63], v[162:163], off offset:64
	global_load_dwordx4 v[66:69], v[166:167], off offset:64
	s_waitcnt lgkmcnt(0)
	s_barrier
	s_waitcnt vmcnt(4)
	ds_write_b128 v81, v[48:51] offset:23552
	s_waitcnt vmcnt(3)
	ds_write_b128 v82, v[52:55] offset:23552
	s_waitcnt vmcnt(2)
	ds_write_b128 v83, v[56:59] offset:23552
	s_waitcnt vmcnt(1)
	ds_write_b128 v78, v[60:63] offset:36864
	s_waitcnt vmcnt(0)
	ds_write_b128 v79, v[66:69] offset:36864
	v_add_u32_e32 v48, 64, v161
	v_mad_i64_i32 v[48:49], s[4:5], v48, s18, v[168:169]
	global_load_dwordx4 v[112:115], v[48:49], off
	v_add_u32_e32 v48, 64, v174
	v_mad_i64_i32 v[48:49], s[4:5], v48, s18, v[170:171]
	global_load_dwordx4 v[116:119], v[48:49], off
	v_add_u32_e32 v48, 64, v175
	v_mad_i64_i32 v[48:49], s[4:5], v48, s18, v[172:173]
	global_load_dwordx4 v[128:131], v[48:49], off
	global_load_dwordx4 v[124:127], v[162:163], off offset:128
	global_load_dwordx4 v[120:123], v[166:167], off offset:128
	v_mul_u32_u24_e32 v70, 0xd0, v64
	v_lshlrev_b32_e32 v185, 1, v70
	v_add_u32_e32 v66, 0x1a00, v185
	v_add_u32_e32 v183, v185, v176
	v_add_u32_e32 v184, v66, v176
	ds_read_b128 v[48:51], v183
	ds_read_b128 v[52:55], v184
	ds_read_b128 v[56:59], v183 offset:64
	v_cndmask_b32_e32 v71, v203, v189, vcc
	v_cmp_lt_i32_e32 vcc, v240, v202
	v_lshlrev_b32_e32 v155, 2, v71
	s_nop 0
	v_cndmask_b32_e32 v71, v203, v240, vcc
	v_lshlrev_b32_e32 v153, 2, v71
	v_readlane_b32 s4, v255, 0
	s_mov_b32 s92, s4
	s_mov_b32 s93, s4
	s_mov_b32 s94, s4
	s_mov_b32 s95, s4
	v_mov_b64_e32 v[60:61], s[92:93]
	v_readlane_b32 s5, v255, 1
	v_readlane_b32 s6, v255, 2
	v_readlane_b32 s7, v255, 3
	v_mov_b64_e32 v[62:63], s[94:95]
	v_writelane_b32 v255, s4, 0
	s_waitcnt lgkmcnt(2)
	v_mfma_f32_16x16x32_bf16 v[68:71], v[48:51], v[40:43], v[60:63]
	v_writelane_b32 v255, s5, 1
	v_writelane_b32 v255, s6, 2
	v_writelane_b32 v255, s7, 3
	v_mfma_f32_16x16x32_bf16 v[48:51], v[48:51], v[44:47], v[60:63]
	ds_read_b128 v[72:75], v184 offset:64
	s_waitcnt lgkmcnt(2)
	v_mfma_f32_16x16x32_bf16 v[76:79], v[52:55], v[40:43], v[60:63]
	v_mfma_f32_16x16x32_bf16 v[52:55], v[52:55], v[44:47], v[60:63]
	s_nop 2
	ds_read_b128 v[60:63], v183 offset:128
	s_waitcnt lgkmcnt(2)
	v_mfma_f32_16x16x32_bf16 v[68:71], v[56:59], v[32:35], v[68:71]
	v_mfma_f32_16x16x32_bf16 v[48:51], v[56:59], v[36:39], v[48:51]
	ds_read_b128 v[56:59], v184 offset:128
	s_waitcnt lgkmcnt(2)
	v_mfma_f32_16x16x32_bf16 v[52:55], v[72:75], v[36:39], v[52:55]
	v_mfma_f32_16x16x32_bf16 v[76:79], v[72:75], v[32:35], v[76:79]
	ds_read_b128 v[72:75], v183 offset:192
	s_waitcnt lgkmcnt(2)
	v_mfma_f32_16x16x32_bf16 v[68:71], v[60:63], v[24:27], v[68:71]
	v_mfma_f32_16x16x32_bf16 v[48:51], v[60:63], v[28:31], v[48:51]
	ds_read_b128 v[60:63], v184 offset:192
	s_waitcnt lgkmcnt(2)
	v_mfma_f32_16x16x32_bf16 v[52:55], v[56:59], v[28:31], v[52:55]
	v_mfma_f32_16x16x32_bf16 v[76:79], v[56:59], v[24:27], v[76:79]
	ds_read_b128 v[56:59], v183 offset:256
	s_waitcnt lgkmcnt(2)
	v_mfma_f32_16x16x32_bf16 v[68:71], v[72:75], v[16:19], v[68:71]
	v_mfma_f32_16x16x32_bf16 v[48:51], v[72:75], v[20:23], v[48:51]
	ds_read_b128 v[72:75], v184 offset:256
	s_waitcnt lgkmcnt(2)
	v_mfma_f32_16x16x32_bf16 v[52:55], v[60:63], v[20:23], v[52:55]
	v_mfma_f32_16x16x32_bf16 v[76:79], v[60:63], v[16:19], v[76:79]
	ds_read_b128 v[80:83], v183 offset:320
	s_waitcnt lgkmcnt(2)
	v_mfma_f32_16x16x32_bf16 v[60:63], v[56:59], v[4:7], v[68:71]
	v_mfma_f32_16x16x32_bf16 v[48:51], v[56:59], v[12:15], v[48:51]
	s_nop 1
	ds_read_b128 v[68:71], v184 offset:320
	s_waitcnt lgkmcnt(2)
	v_mfma_f32_16x16x32_bf16 v[56:59], v[72:75], v[4:7], v[76:79]
	v_mfma_f32_16x16x32_bf16 v[72:75], v[72:75], v[12:15], v[52:55]
	s_waitcnt lgkmcnt(1)
	v_mfma_f32_16x16x32_bf16 v[60:63], v[80:83], v[0:3], v[60:63]
	v_mfma_f32_16x16x32_bf16 v[52:55], v[80:83], v[8:11], v[48:51]
	s_waitcnt lgkmcnt(0)
	v_mfma_f32_16x16x32_bf16 v[56:59], v[68:71], v[0:3], v[56:59]
	v_mfma_f32_16x16x32_bf16 v[48:51], v[68:71], v[8:11], v[72:75]
	s_nop 3
	v_max_f32_e32 v67, v61, v61
	v_max_f32_e32 v68, v60, v60
	v_max_f32_e32 v67, v68, v67
	v_max3_f32 v67, v67, v62, v63
	v_max3_f32 v67, v67, v56, v57
	v_max3_f32 v67, v67, v58, v59
	ds_bpermute_b32 v68, v155, v67
	v_mov_b32_e32 v186, 0
	s_cmp_eq_u64 exec, 0
	v_mov_b32_e32 v187, 0
	s_waitcnt lgkmcnt(0)
	v_max_f32_e32 v68, v68, v68
	v_max_f32_e32 v67, v67, v68
	ds_bpermute_b32 v68, v153, v67
	s_cbranch_scc1 .LBB0_357
	s_waitcnt lgkmcnt(0)
	v_max_f32_e32 v68, v68, v68
	v_max_f32_e32 v67, v67, v67
	v_max_f32_e32 v67, v67, v68
	v_add_f32_e32 v187, 0, v67
	v_sub_f32_e32 v60, v60, v67
	v_sub_f32_e32 v61, v61, v67
	v_sub_f32_e32 v62, v62, v67
	v_sub_f32_e32 v63, v63, v67
	v_sub_f32_e32 v56, v56, v67
	v_sub_f32_e32 v57, v57, v67
	v_sub_f32_e32 v58, v58, v67
	v_sub_f32_e32 v59, v59, v67

.LBB0_370:
	s_and_b64 vcc, exec, s[4:5]
	s_cbranch_vccz .LBB0_353
	s_ashr_i32 s4, s22, 3
	s_lshl_b32 s6, s4, 1
	s_and_b32 s5, s4, -16
	s_and_b32 s6, s6, 14
	s_or_b32 s5, s6, s5
	s_bfe_u32 s6, s4, 0x10003
	s_or_b32 s5, s5, s6
	s_cmp_lt_i32 s4, 0
	s_cselect_b32 s30, s5, s4
	s_lshl_b32 s4, s22, 5
	s_and_b32 s4, s4, 0xe0
	s_add_i32 s4, s30, s4
	s_ashr_i32 s31, s4, 6
	s_bfe_u32 s23, s4, 0x30003
	s_lshl_b32 s4, s31, 3
	s_or_b32 s6, s4, s23
	s_mul_i32 s4, s6, 0x78000
	s_mul_hi_i32 s5, s6, 0x78000
	s_add_u32 s4, s14, s4
	s_addc_u32 s5, s15, s5
	s_mul_hi_i32 s7, s6, 0x50000
	s_mul_i32 s6, s6, 0x50000
	s_add_u32 s6, s16, s6
	s_addc_u32 s7, s17, s7
	s_lshl_b32 s30, s30, 7
	s_lshl_b32 s31, s31, 10
	s_and_b32 s30, s30, 0x380
	v_mov_b32_e32 v60, v188
	s_or_b32 s30, s31, s30
	s_addk_i32 s30, 0x1000
	v_and_b32_e32 v64, 15, v60
	v_ashrrev_i32_e32 v0, 1, v60
	v_or_b32_e32 v1, s30, v64
	s_mul_i32 s30, s23, 0x180
	v_bfe_u32 v65, v60, 4, 2
	v_and_b32_e32 v0, 0xffffffe0, v0
	s_add_u32 s30, s8, s30
	v_add_u32_e32 v150, v1, v0
	s_addc_u32 s31, s9, 0
	v_lshlrev_b32_e32 v176, 4, v65
	v_lshl_add_u64 v[8:9], s[30:31], 0, v[176:177]
	s_movk_i32 s36, 0xc00
	v_or_b32_e32 v148, 16, v150
	v_mad_i64_i32 v[0:1], s[30:31], v150, s36, v[8:9]
	v_mad_i64_i32 v[8:9], s[30:31], v148, s36, v[8:9]
	s_mov_b32 s36, 0x2aaaaaab
	v_mul_hi_i32 v48, v60, s36
	s_waitcnt lgkmcnt(0)
	v_lshrrev_b32_e32 v49, 31, v48
	v_ashrrev_i32_e32 v48, 2, v48
	v_add_u32_e32 v161, v48, v49
	v_mul_lo_u32 v48, v161, 24
	v_add_u32_e32 v68, 0x100, v60
	v_add_u32_e32 v56, 0x200, v60
	v_sub_u32_e32 v78, v60, v48
	v_mul_hi_i32 v52, v68, s36
	v_mul_hi_i32 v57, v56, s36
	v_lshlrev_b32_e32 v152, 3, v78
	v_lshrrev_b32_e32 v53, 31, v52
	v_ashrrev_i32_e32 v52, 2, v52
	v_lshrrev_b32_e32 v58, 31, v57
	v_ashrrev_i32_e32 v57, 2, v57
	v_mov_b64_e32 v[70:71], s[4:5]
	v_ashrrev_i32_e32 v153, 31, v152
	v_add_u32_e32 v174, v52, v53
	v_add_u32_e32 v175, v57, v58
	v_mad_i64_i32 v[48:49], s[30:31], v161, s18, v[70:71]
	v_lshlrev_b64 v[72:73], 1, v[152:153]
	s_mul_i32 m0, s23, 0x78000
	v_cmp_le_u32_e32 vcc, 0x80, v152
	v_mov_b32_e32 v73, m0
	s_nop 1
	v_cndmask_b32_e32 v73, 0, v73, vcc
	v_sub_u32_e32 v72, v72, v73
	v_ashrrev_i32_e32 v73, 31, v72
	v_mul_lo_u32 v52, v174, 24
	v_mul_lo_u32 v57, v175, 24
	v_ashrrev_i32_e32 v61, 31, v60
	v_ashrrev_i32_e32 v69, 31, v68
	v_lshl_add_u64 v[48:49], v[48:49], 0, v[72:73]
	v_sub_u32_e32 v79, v68, v52
	v_sub_u32_e32 v80, v56, v57
	v_lshrrev_b32_e32 v61, 30, v61
	v_lshrrev_b32_e32 v69, 30, v69
	global_load_dwordx4 v[40:43], v[0:1], off
	global_load_dwordx4 v[32:35], v[0:1], off offset:64
	global_load_dwordx4 v[24:27], v[0:1], off offset:128
	global_load_dwordx4 v[16:19], v[0:1], off offset:192
	global_load_dwordx4 v[4:7], v[0:1], off offset:256
	s_nop 0
	global_load_dwordx4 v[0:3], v[0:1], off offset:320
	s_nop 0
	global_load_dwordx4 v[44:47], v[8:9], off
	global_load_dwordx4 v[36:39], v[8:9], off offset:64
	global_load_dwordx4 v[28:31], v[8:9], off offset:128
	global_load_dwordx4 v[20:23], v[8:9], off offset:192
	global_load_dwordx4 v[12:15], v[8:9], off offset:256
	s_nop 0
	global_load_dwordx4 v[8:11], v[8:9], off offset:320
	v_lshlrev_b32_e32 v154, 3, v79
	global_load_dwordx4 v[48:51], v[48:49], off
	v_lshlrev_b32_e32 v156, 3, v80
	v_add_u32_e32 v61, v60, v61
	v_add_u32_e32 v69, v68, v69
	v_ashrrev_i32_e32 v155, 31, v154
	v_ashrrev_i32_e32 v157, 31, v156
	v_ashrrev_i32_e32 v81, 2, v61
	v_and_b32_e32 v61, -4, v61
	v_ashrrev_i32_e32 v83, 2, v69
	v_and_b32_e32 v69, -4, v69
	v_mad_i64_i32 v[52:53], s[30:31], v174, s18, v[70:71]
	v_lshlrev_b64 v[74:75], 1, v[154:155]
	s_mul_i32 m0, s23, 0x78000
	v_cmp_le_u32_e32 vcc, 0x80, v154
	v_mov_b32_e32 v75, m0
	s_nop 1
	v_cndmask_b32_e32 v75, 0, v75, vcc
	v_sub_u32_e32 v74, v74, v75
	v_ashrrev_i32_e32 v75, 31, v74
	v_mad_i64_i32 v[56:57], s[30:31], v175, s18, v[70:71]
	v_lshlrev_b64 v[76:77], 1, v[156:157]
	s_mul_i32 m0, s23, 0x78000
	v_cmp_le_u32_e32 vcc, 0x80, v156
	v_mov_b32_e32 v77, m0
	s_nop 1
	v_cndmask_b32_e32 v77, 0, v77, vcc
	v_sub_u32_e32 v76, v76, v77
	v_ashrrev_i32_e32 v77, 31, v76
	v_sub_u32_e32 v82, v60, v61
	v_sub_u32_e32 v84, v68, v69
	v_lshl_add_u64 v[52:53], v[52:53], 0, v[74:75]
	v_lshl_add_u64 v[56:57], v[56:57], 0, v[76:77]
	v_mov_b64_e32 v[66:67], s[6:7]
	s_movk_i32 s30, 0xa00
	v_lshlrev_b32_e32 v158, 3, v82
	v_lshlrev_b32_e32 v164, 3, v84
	global_load_dwordx4 v[52:55], v[52:53], off
	v_mad_i64_i32 v[60:61], s[6:7], v81, s30, v[66:67]
	global_load_dwordx4 v[56:59], v[56:57], off
	v_ashrrev_i32_e32 v159, 31, v158
	v_mad_i64_i32 v[66:67], s[6:7], v83, s30, v[66:67]
	v_ashrrev_i32_e32 v165, 31, v164
	v_lshl_add_u64 v[162:163], v[158:159], 1, v[60:61]
	v_lshl_add_u64 v[166:167], v[164:165], 1, v[66:67]
	global_load_dwordx4 v[60:63], v[162:163], off
	global_load_dwordx4 v[66:69], v[166:167], off
	s_movk_i32 s6, 0xd0
	v_mul_lo_u32 v178, v161, s6
	v_lshlrev_b32_e32 v78, 4, v78
	v_lshl_add_u32 v78, v178, 1, v78
	s_barrier
	v_mul_lo_u32 v179, v174, s6
	v_mul_lo_u32 v180, v175, s6
	v_mul_lo_u32 v181, v81, 40
	v_mul_lo_u32 v182, v83, 40
	v_lshl_add_u64 v[168:169], s[4:5], 0, v[72:73]
	v_lshl_add_u64 v[170:171], s[4:5], 0, v[74:75]
	v_lshl_add_u64 v[172:173], s[4:5], 0, v[76:77]
	v_cmp_lt_i32_e32 vcc, v189, v202
	s_waitcnt vmcnt(4)
	ds_write_b128 v78, v[48:51]
	v_lshlrev_b32_e32 v48, 4, v79
	v_lshl_add_u32 v79, v179, 1, v48
	v_lshlrev_b32_e32 v48, 4, v80
	v_lshl_add_u32 v80, v180, 1, v48
	v_lshlrev_b32_e32 v48, 4, v82
	v_lshl_add_u32 v81, v181, 1, v48
	v_lshlrev_b32_e32 v48, 4, v84
	v_lshl_add_u32 v82, v182, 1, v48
	v_add_u32_e32 v48, 32, v161
	v_mad_i64_i32 v[48:49], s[6:7], v48, s18, v[70:71]
	v_lshl_add_u64 v[48:49], v[48:49], 0, v[72:73]
	global_load_dwordx4 v[48:51], v[48:49], off
	s_waitcnt vmcnt(4)
	ds_write_b128 v79, v[52:55]
	v_add_u32_e32 v52, 32, v174
	v_mad_i64_i32 v[52:53], s[6:7], v52, s18, v[70:71]
	s_waitcnt vmcnt(3)
	ds_write_b128 v80, v[56:59]
	v_add_u32_e32 v56, 32, v175
	v_mad_i64_i32 v[56:57], s[6:7], v56, s18, v[70:71]
	v_lshl_add_u64 v[52:53], v[52:53], 0, v[74:75]
	v_lshl_add_u64 v[56:57], v[56:57], 0, v[76:77]
	s_waitcnt vmcnt(2)
	ds_write_b128 v81, v[60:63] offset:13312
	s_waitcnt vmcnt(1)
	ds_write_b128 v82, v[66:69] offset:13312
	global_load_dwordx4 v[52:55], v[52:53], off
	s_nop 0
	global_load_dwordx4 v[56:59], v[56:57], off
	s_nop 0
	global_load_dwordx4 v[60:63], v[162:163], off offset:64
	global_load_dwordx4 v[66:69], v[166:167], off offset:64
	s_waitcnt lgkmcnt(0)
	s_barrier
	s_waitcnt vmcnt(4)
	ds_write_b128 v78, v[48:51] offset:23552
	s_waitcnt vmcnt(3)
	ds_write_b128 v79, v[52:55] offset:23552
	s_waitcnt vmcnt(2)
	ds_write_b128 v80, v[56:59] offset:23552
	s_waitcnt vmcnt(1)
	ds_write_b128 v81, v[60:63] offset:36864
	s_waitcnt vmcnt(0)
	ds_write_b128 v82, v[66:69] offset:36864
	v_add_u32_e32 v48, 64, v161
	v_mad_i64_i32 v[48:49], s[4:5], v48, s18, v[168:169]
	global_load_dwordx4 v[112:115], v[48:49], off
	v_add_u32_e32 v48, 64, v174
	v_mad_i64_i32 v[48:49], s[4:5], v48, s18, v[170:171]
	global_load_dwordx4 v[116:119], v[48:49], off
	v_add_u32_e32 v48, 64, v175
	v_mad_i64_i32 v[48:49], s[4:5], v48, s18, v[172:173]
	global_load_dwordx4 v[128:131], v[48:49], off
	global_load_dwordx4 v[124:127], v[162:163], off offset:128
	global_load_dwordx4 v[120:123], v[166:167], off offset:128
	v_mul_u32_u24_e32 v70, 0xd0, v64
	v_lshlrev_b32_e32 v185, 1, v70
	v_add_u32_e32 v66, 0x1a00, v185
	v_add_u32_e32 v183, v185, v176
	v_add_u32_e32 v184, v66, v176
	ds_read_b128 v[48:51], v183
	ds_read_b128 v[52:55], v184
	ds_read_b128 v[56:59], v183 offset:64
	v_cndmask_b32_e32 v71, v203, v189, vcc
	v_cmp_lt_i32_e32 vcc, v240, v202
	v_lshlrev_b32_e32 v155, 2, v71
	s_nop 0
	v_cndmask_b32_e32 v71, v203, v240, vcc
	v_lshlrev_b32_e32 v153, 2, v71
	v_readlane_b32 s4, v255, 0
	s_mov_b32 s92, s4
	s_mov_b32 s93, s4
	s_mov_b32 s94, s4
	s_mov_b32 s95, s4
	v_mov_b64_e32 v[60:61], s[92:93]
	v_readlane_b32 s5, v255, 1
	v_readlane_b32 s6, v255, 2
	v_readlane_b32 s7, v255, 3
	v_mov_b64_e32 v[62:63], s[94:95]
	v_writelane_b32 v255, s4, 0
	s_waitcnt lgkmcnt(2)
	v_mfma_f32_16x16x32_bf16 v[68:71], v[48:51], v[40:43], v[60:63]
	v_writelane_b32 v255, s5, 1
	v_writelane_b32 v255, s6, 2
	v_writelane_b32 v255, s7, 3
	v_mfma_f32_16x16x32_bf16 v[48:51], v[48:51], v[44:47], v[60:63]
	ds_read_b128 v[72:75], v184 offset:64
	s_waitcnt lgkmcnt(2)
	v_mfma_f32_16x16x32_bf16 v[76:79], v[52:55], v[40:43], v[60:63]
	v_mfma_f32_16x16x32_bf16 v[52:55], v[52:55], v[44:47], v[60:63]
	s_nop 2
	ds_read_b128 v[60:63], v183 offset:128
	s_waitcnt lgkmcnt(2)
	v_mfma_f32_16x16x32_bf16 v[68:71], v[56:59], v[32:35], v[68:71]
	v_mfma_f32_16x16x32_bf16 v[48:51], v[56:59], v[36:39], v[48:51]
	ds_read_b128 v[56:59], v184 offset:128
	s_waitcnt lgkmcnt(2)
	v_mfma_f32_16x16x32_bf16 v[52:55], v[72:75], v[36:39], v[52:55]
	v_mfma_f32_16x16x32_bf16 v[76:79], v[72:75], v[32:35], v[76:79]
	ds_read_b128 v[72:75], v183 offset:192
	s_waitcnt lgkmcnt(2)
	v_mfma_f32_16x16x32_bf16 v[68:71], v[60:63], v[24:27], v[68:71]
	v_mfma_f32_16x16x32_bf16 v[48:51], v[60:63], v[28:31], v[48:51]
	ds_read_b128 v[60:63], v184 offset:192
	s_waitcnt lgkmcnt(2)
	v_mfma_f32_16x16x32_bf16 v[52:55], v[56:59], v[28:31], v[52:55]
	v_mfma_f32_16x16x32_bf16 v[76:79], v[56:59], v[24:27], v[76:79]
	ds_read_b128 v[56:59], v183 offset:256
	s_waitcnt lgkmcnt(2)
	v_mfma_f32_16x16x32_bf16 v[68:71], v[72:75], v[16:19], v[68:71]
	v_mfma_f32_16x16x32_bf16 v[48:51], v[72:75], v[20:23], v[48:51]
	ds_read_b128 v[72:75], v184 offset:256
	s_waitcnt lgkmcnt(2)
	v_mfma_f32_16x16x32_bf16 v[52:55], v[60:63], v[20:23], v[52:55]
	v_mfma_f32_16x16x32_bf16 v[76:79], v[60:63], v[16:19], v[76:79]
	ds_read_b128 v[80:83], v183 offset:320
	s_waitcnt lgkmcnt(2)
	v_mfma_f32_16x16x32_bf16 v[60:63], v[56:59], v[4:7], v[68:71]
	v_mfma_f32_16x16x32_bf16 v[48:51], v[56:59], v[12:15], v[48:51]
	s_nop 1
	ds_read_b128 v[68:71], v184 offset:320
	s_waitcnt lgkmcnt(2)
	v_mfma_f32_16x16x32_bf16 v[56:59], v[72:75], v[4:7], v[76:79]
	v_mfma_f32_16x16x32_bf16 v[72:75], v[72:75], v[12:15], v[52:55]
	s_waitcnt lgkmcnt(1)
	v_mfma_f32_16x16x32_bf16 v[60:63], v[80:83], v[0:3], v[60:63]
	v_mfma_f32_16x16x32_bf16 v[52:55], v[80:83], v[8:11], v[48:51]
	s_waitcnt lgkmcnt(0)
	v_mfma_f32_16x16x32_bf16 v[56:59], v[68:71], v[0:3], v[56:59]
	v_mfma_f32_16x16x32_bf16 v[48:51], v[68:71], v[8:11], v[72:75]
	s_nop 3
	v_max_f32_e32 v67, v61, v61
	v_max_f32_e32 v68, v60, v60
	v_max_f32_e32 v67, v68, v67
	v_max3_f32 v67, v67, v62, v63
	v_max3_f32 v67, v67, v56, v57
	v_max3_f32 v67, v67, v58, v59
	ds_bpermute_b32 v68, v155, v67
	v_mov_b32_e32 v186, 0
	s_cmp_eq_u64 exec, 0
	v_mov_b32_e32 v187, 0
	s_waitcnt lgkmcnt(0)
	v_max_f32_e32 v68, v68, v68
	v_max_f32_e32 v67, v67, v68
	ds_bpermute_b32 v68, v153, v67
	s_cbranch_scc1 .LBB0_373
	s_waitcnt lgkmcnt(0)
	v_max_f32_e32 v68, v68, v68
	v_max_f32_e32 v67, v67, v67
	v_max_f32_e32 v67, v67, v68
	v_add_f32_e32 v187, 0, v67
	v_sub_f32_e32 v60, v60, v67
	v_sub_f32_e32 v61, v61, v67
	v_sub_f32_e32 v62, v62, v67
	v_sub_f32_e32 v63, v63, v67
	v_sub_f32_e32 v56, v56, v67
	v_sub_f32_e32 v57, v57, v67
	v_sub_f32_e32 v58, v58, v67
	v_sub_f32_e32 v59, v59, v67

.LBB0_499:
	s_or_b64 exec, exec, vcc
	v_lshlrev_b32_e32 v184, 1, v128
	v_mov_b32_e32 v185, v177
	v_lshl_add_u64 v[152:153], v[152:153], 0, v[184:185]
	v_cvt_pk_bf16_f32 v124, v124, v125
	v_cvt_pk_bf16_f32 v125, v126, v127
	v_lshl_add_u64 v[126:127], v[152:153], 0, v[174:175]
	v_lshl_add_u64 v[126:127], v[152:153], 0, v[172:173]
	v_lshl_add_u64 v[126:127], v[152:153], 0, v[170:171]
	v_lshl_add_u64 v[126:127], v[152:153], 0, v[168:169]
	v_lshl_add_u64 v[126:127], v[152:153], 0, v[166:167]
	v_lshl_add_u64 v[126:127], v[152:153], 0, v[164:165]
	v_lshl_add_u64 v[126:127], v[152:153], 0, v[162:163]
	v_lshl_add_u64 v[126:127], v[152:153], 0, v[160:161]
	v_lshl_add_u64 v[126:127], v[152:153], 0, v[158:159]
	v_lshl_add_u64 v[126:127], v[152:153], 0, v[156:157]
	v_lshl_add_u64 v[126:127], v[152:153], 0, v[154:155]
	v_lshl_add_u64 v[126:127], v[152:153], 0, v[150:151]
	v_lshl_add_u64 v[126:127], v[152:153], 0, v[148:149]
	global_store_dwordx2 v[152:153], v[124:125], off
	v_lshl_add_u64 v[126:127], v[152:153], 0, v[146:147]
	v_or_b32_e32 v124, 16, v128
	v_lshlrev_b32_e32 v126, 1, v124
	v_cvt_pk_bf16_f32 v124, v120, v121
	v_cvt_pk_bf16_f32 v125, v122, v123
	s_and_saveexec_b64 s[58:59], s[44:45]
	s_xor_b64 s[58:59], exec, s[58:59]
	s_cbranch_execz .LBB0_501
	v_lshlrev_b32_e32 v146, 2, v128
	v_mov_b32_e32 v147, v177
	v_lshl_add_u64 v[146:147], v[142:143], 0, v[146:147]
	v_mov_b32_e32 v127, v177
	global_store_dwordx4 v[146:147], v[120:123], off offset:64
	s_nop 1
	v_lshl_add_u64 v[120:121], v[140:141], 0, v[126:127]
	v_add_co_u32_e32 v122, vcc, 0x5100000, v120
	s_nop 1
	v_addc_co_u32_e32 v123, vcc, 0, v121, vcc
	global_store_dwordx2 v[122:123], v[124:125], off offset:256
	v_add_co_u32_e32 v122, vcc, 0x5118000, v120
	s_nop 1
	v_addc_co_u32_e32 v123, vcc, 0, v121, vcc
	v_add_co_u32_e32 v122, vcc, 0x5130000, v120
	s_nop 1
	v_addc_co_u32_e32 v123, vcc, 0, v121, vcc
	v_add_co_u32_e32 v122, vcc, 0x5148000, v120
	s_nop 1
	v_addc_co_u32_e32 v123, vcc, 0, v121, vcc
	v_add_co_u32_e32 v122, vcc, 0x5160000, v120
	s_nop 1
	v_addc_co_u32_e32 v123, vcc, 0, v121, vcc
	v_add_co_u32_e32 v122, vcc, 0x5178000, v120
	s_nop 1
	v_addc_co_u32_e32 v123, vcc, 0, v121, vcc
	v_add_co_u32_e32 v122, vcc, 0x5190000, v120
	s_nop 1
	v_addc_co_u32_e32 v123, vcc, 0, v121, vcc
	v_add_co_u32_e32 v120, vcc, 0x51a8000, v120
	s_nop 0
	v_addc_co_u32_e32 v121, vcc, 0, v121, vcc
.LBB0_501:
	s_andn2_saveexec_b64 s[58:59], s[58:59]
	s_cbranch_execz .LBB0_503
	v_mov_b32_e32 v127, v177
	v_lshl_add_u64 v[120:121], v[144:145], 0, v[126:127]
	v_add_co_u32_e32 v122, vcc, 0xb900000, v120
	s_nop 1
	v_addc_co_u32_e32 v123, vcc, 0, v121, vcc
	global_store_dwordx2 v[122:123], v[124:125], off offset:256
	v_add_co_u32_e32 v122, vcc, 0xb978000, v120
	s_nop 1
	v_addc_co_u32_e32 v123, vcc, 0, v121, vcc
	v_add_co_u32_e32 v122, vcc, 0xb9f0000, v120
	s_nop 1
	v_addc_co_u32_e32 v123, vcc, 0, v121, vcc
	v_add_co_u32_e32 v122, vcc, 0xba68000, v120
	s_nop 1
	v_addc_co_u32_e32 v123, vcc, 0, v121, vcc
	v_add_co_u32_e32 v122, vcc, 0xbae0000, v120
	s_nop 1
	v_addc_co_u32_e32 v123, vcc, 0, v121, vcc
	v_add_co_u32_e32 v122, vcc, 0xbb58000, v120
	s_nop 1
	v_addc_co_u32_e32 v123, vcc, 0, v121, vcc
	v_add_co_u32_e32 v122, vcc, 0xbbd0000, v120
	s_nop 1
	v_addc_co_u32_e32 v123, vcc, 0, v121, vcc
	v_add_co_u32_e32 v120, vcc, 0xbc48000, v120
	s_nop 0
	v_addc_co_u32_e32 v121, vcc, 0, v121, vcc
.LBB0_503:
	s_or_b64 exec, exec, s[58:59]
	v_or_b32_e32 v120, 32, v128
	v_lshlrev_b32_e32 v122, 1, v120
	v_cvt_pk_bf16_f32 v120, v116, v117
	v_cvt_pk_bf16_f32 v121, v118, v119
	s_and_saveexec_b64 s[58:59], s[44:45]
	s_xor_b64 s[58:59], exec, s[58:59]
	s_cbranch_execz .LBB0_505
	v_lshlrev_b32_e32 v124, 2, v128
	v_mov_b32_e32 v125, v177
	v_lshl_add_u64 v[124:125], v[142:143], 0, v[124:125]
	v_mov_b32_e32 v123, v177
	global_store_dwordx4 v[124:125], v[116:119], off offset:128
	s_nop 1
	v_lshl_add_u64 v[116:117], v[140:141], 0, v[122:123]
	v_add_co_u32_e32 v118, vcc, 0x5100000, v116
	s_nop 1
	v_addc_co_u32_e32 v119, vcc, 0, v117, vcc
	global_store_dwordx2 v[118:119], v[120:121], off offset:256
	v_add_co_u32_e32 v118, vcc, 0x5118000, v116
	s_nop 1
	v_addc_co_u32_e32 v119, vcc, 0, v117, vcc
	v_add_co_u32_e32 v118, vcc, 0x5130000, v116
	s_nop 1
	v_addc_co_u32_e32 v119, vcc, 0, v117, vcc
	v_add_co_u32_e32 v118, vcc, 0x5148000, v116
	s_nop 1
	v_addc_co_u32_e32 v119, vcc, 0, v117, vcc
	v_add_co_u32_e32 v118, vcc, 0x5160000, v116
	s_nop 1
	v_addc_co_u32_e32 v119, vcc, 0, v117, vcc
	v_add_co_u32_e32 v118, vcc, 0x5178000, v116
	s_nop 1
	v_addc_co_u32_e32 v119, vcc, 0, v117, vcc
	v_add_co_u32_e32 v118, vcc, 0x5190000, v116
	s_nop 1
	v_addc_co_u32_e32 v119, vcc, 0, v117, vcc
	v_add_co_u32_e32 v116, vcc, 0x51a8000, v116
	s_nop 0
	v_addc_co_u32_e32 v117, vcc, 0, v117, vcc
.LBB0_505:
	s_andn2_saveexec_b64 s[58:59], s[58:59]
	s_cbranch_execz .LBB0_507
	v_mov_b32_e32 v123, v177
	v_lshl_add_u64 v[116:117], v[144:145], 0, v[122:123]
	v_add_co_u32_e32 v118, vcc, 0xb900000, v116
	s_nop 1
	v_addc_co_u32_e32 v119, vcc, 0, v117, vcc
	global_store_dwordx2 v[118:119], v[120:121], off offset:256
	v_add_co_u32_e32 v118, vcc, 0xb978000, v116
	s_nop 1
	v_addc_co_u32_e32 v119, vcc, 0, v117, vcc
	v_add_co_u32_e32 v118, vcc, 0xb9f0000, v116
	s_nop 1
	v_addc_co_u32_e32 v119, vcc, 0, v117, vcc
	v_add_co_u32_e32 v118, vcc, 0xba68000, v116
	s_nop 1
	v_addc_co_u32_e32 v119, vcc, 0, v117, vcc
	v_add_co_u32_e32 v118, vcc, 0xbae0000, v116
	s_nop 1
	v_addc_co_u32_e32 v119, vcc, 0, v117, vcc
	v_add_co_u32_e32 v118, vcc, 0xbb58000, v116
	s_nop 1
	v_addc_co_u32_e32 v119, vcc, 0, v117, vcc
	v_add_co_u32_e32 v118, vcc, 0xbbd0000, v116
	s_nop 1
	v_addc_co_u32_e32 v119, vcc, 0, v117, vcc
	v_add_co_u32_e32 v116, vcc, 0xbc48000, v116
	s_nop 0
	v_addc_co_u32_e32 v117, vcc, 0, v117, vcc
.LBB0_507:
	s_or_b64 exec, exec, s[58:59]
	v_or_b32_e32 v116, 48, v128
	v_lshlrev_b32_e32 v118, 1, v116
	v_cvt_pk_bf16_f32 v116, v112, v113
	v_cvt_pk_bf16_f32 v117, v114, v115
	s_and_saveexec_b64 s[58:59], s[44:45]
	s_xor_b64 s[58:59], exec, s[58:59]
	s_cbranch_execz .LBB0_509
	v_lshlrev_b32_e32 v120, 2, v128
	v_mov_b32_e32 v121, v177
	v_lshl_add_u64 v[120:121], v[142:143], 0, v[120:121]
	v_mov_b32_e32 v119, v177
	global_store_dwordx4 v[120:121], v[112:115], off offset:192
	s_nop 1
	v_lshl_add_u64 v[112:113], v[140:141], 0, v[118:119]
	v_add_co_u32_e32 v114, vcc, 0x5100000, v112
	s_nop 1
	v_addc_co_u32_e32 v115, vcc, 0, v113, vcc
	global_store_dwordx2 v[114:115], v[116:117], off offset:256
	v_add_co_u32_e32 v114, vcc, 0x5118000, v112
	s_nop 1
	v_addc_co_u32_e32 v115, vcc, 0, v113, vcc
	v_add_co_u32_e32 v114, vcc, 0x5130000, v112
	s_nop 1
	v_addc_co_u32_e32 v115, vcc, 0, v113, vcc
	v_add_co_u32_e32 v114, vcc, 0x5148000, v112
	s_nop 1
	v_addc_co_u32_e32 v115, vcc, 0, v113, vcc
	v_add_co_u32_e32 v114, vcc, 0x5160000, v112
	s_nop 1
	v_addc_co_u32_e32 v115, vcc, 0, v113, vcc
	v_add_co_u32_e32 v114, vcc, 0x5178000, v112
	s_nop 1
	v_addc_co_u32_e32 v115, vcc, 0, v113, vcc
	v_add_co_u32_e32 v114, vcc, 0x5190000, v112
	s_nop 1
	v_addc_co_u32_e32 v115, vcc, 0, v113, vcc
	v_add_co_u32_e32 v112, vcc, 0x51a8000, v112
	s_nop 0
	v_addc_co_u32_e32 v113, vcc, 0, v113, vcc
.LBB0_509:
	s_andn2_saveexec_b64 s[58:59], s[58:59]
	s_cbranch_execz .LBB0_511
	v_mov_b32_e32 v119, v177
	v_lshl_add_u64 v[112:113], v[144:145], 0, v[118:119]
	v_add_co_u32_e32 v114, vcc, 0xb900000, v112
	s_nop 1
	v_addc_co_u32_e32 v115, vcc, 0, v113, vcc
	global_store_dwordx2 v[114:115], v[116:117], off offset:256
	v_add_co_u32_e32 v114, vcc, 0xb978000, v112
	s_nop 1
	v_addc_co_u32_e32 v115, vcc, 0, v113, vcc
	v_add_co_u32_e32 v114, vcc, 0xb9f0000, v112
	s_nop 1
	v_addc_co_u32_e32 v115, vcc, 0, v113, vcc
	v_add_co_u32_e32 v114, vcc, 0xba68000, v112
	s_nop 1
	v_addc_co_u32_e32 v115, vcc, 0, v113, vcc
	v_add_co_u32_e32 v114, vcc, 0xbae0000, v112
	s_nop 1
	v_addc_co_u32_e32 v115, vcc, 0, v113, vcc
	v_add_co_u32_e32 v114, vcc, 0xbb58000, v112
	s_nop 1
	v_addc_co_u32_e32 v115, vcc, 0, v113, vcc
	v_add_co_u32_e32 v114, vcc, 0xbbd0000, v112
	s_nop 1
	v_addc_co_u32_e32 v115, vcc, 0, v113, vcc
	v_add_co_u32_e32 v112, vcc, 0xbc48000, v112
	s_nop 0
	v_addc_co_u32_e32 v113, vcc, 0, v113, vcc

.LBB0_535:
	s_or_b64 exec, exec, vcc
	v_lshlrev_b32_e32 v164, 1, v128
	v_mov_b32_e32 v165, v177
	v_lshl_add_u64 v[124:125], v[124:125], 0, v[164:165]
	v_cvt_pk_bf16_f32 v108, v108, v109
	v_cvt_pk_bf16_f32 v109, v110, v111
	v_lshl_add_u64 v[110:111], v[124:125], 0, v[158:159]
	v_lshl_add_u64 v[110:111], v[124:125], 0, v[156:157]
	v_lshl_add_u64 v[110:111], v[124:125], 0, v[154:155]
	v_lshl_add_u64 v[110:111], v[124:125], 0, v[152:153]
	v_lshl_add_u64 v[110:111], v[124:125], 0, v[150:151]
	v_lshl_add_u64 v[110:111], v[124:125], 0, v[148:149]
	v_lshl_add_u64 v[110:111], v[124:125], 0, v[146:147]
	v_lshl_add_u64 v[110:111], v[124:125], 0, v[144:145]
	v_lshl_add_u64 v[110:111], v[124:125], 0, v[142:143]
	v_lshl_add_u64 v[110:111], v[124:125], 0, v[140:141]
	v_lshl_add_u64 v[110:111], v[124:125], 0, v[126:127]
	v_lshl_add_u64 v[110:111], v[124:125], 0, v[122:123]
	v_lshl_add_u64 v[110:111], v[124:125], 0, v[120:121]
	global_store_dwordx2 v[124:125], v[108:109], off
	v_lshl_add_u64 v[110:111], v[124:125], 0, v[118:119]
	v_or_b32_e32 v108, 16, v128
	v_lshlrev_b32_e32 v110, 1, v108
	v_cvt_pk_bf16_f32 v108, v104, v105
	v_cvt_pk_bf16_f32 v109, v106, v107
	s_and_saveexec_b64 s[58:59], s[44:45]
	s_xor_b64 s[58:59], exec, s[58:59]
	s_cbranch_execz .LBB0_537
	v_lshlrev_b32_e32 v118, 2, v128
	v_mov_b32_e32 v119, v177
	v_lshl_add_u64 v[118:119], v[114:115], 0, v[118:119]
	v_mov_b32_e32 v111, v177
	global_store_dwordx4 v[118:119], v[104:107], off offset:64
	s_nop 1
	v_lshl_add_u64 v[104:105], v[112:113], 0, v[110:111]
	v_add_co_u32_e32 v106, vcc, 0x5100000, v104
	s_nop 1
	v_addc_co_u32_e32 v107, vcc, 0, v105, vcc
	global_store_dwordx2 v[106:107], v[108:109], off offset:256
	v_add_co_u32_e32 v106, vcc, 0x5118000, v104
	s_nop 1
	v_addc_co_u32_e32 v107, vcc, 0, v105, vcc
	v_add_co_u32_e32 v106, vcc, 0x5130000, v104
	s_nop 1
	v_addc_co_u32_e32 v107, vcc, 0, v105, vcc
	v_add_co_u32_e32 v106, vcc, 0x5148000, v104
	s_nop 1
	v_addc_co_u32_e32 v107, vcc, 0, v105, vcc
	v_add_co_u32_e32 v106, vcc, 0x5160000, v104
	s_nop 1
	v_addc_co_u32_e32 v107, vcc, 0, v105, vcc
	v_add_co_u32_e32 v106, vcc, 0x5178000, v104
	s_nop 1
	v_addc_co_u32_e32 v107, vcc, 0, v105, vcc
	v_add_co_u32_e32 v106, vcc, 0x5190000, v104
	s_nop 1
	v_addc_co_u32_e32 v107, vcc, 0, v105, vcc
	v_add_co_u32_e32 v104, vcc, 0x51a8000, v104
	s_nop 0
	v_addc_co_u32_e32 v105, vcc, 0, v105, vcc
.LBB0_537:
	s_andn2_saveexec_b64 s[58:59], s[58:59]
	s_cbranch_execz .LBB0_539
	v_mov_b32_e32 v111, v177
	v_lshl_add_u64 v[104:105], v[116:117], 0, v[110:111]
	v_add_co_u32_e32 v106, vcc, 0xb900000, v104
	s_nop 1
	v_addc_co_u32_e32 v107, vcc, 0, v105, vcc
	global_store_dwordx2 v[106:107], v[108:109], off offset:256
	v_add_co_u32_e32 v106, vcc, 0xb978000, v104
	s_nop 1
	v_addc_co_u32_e32 v107, vcc, 0, v105, vcc
	v_add_co_u32_e32 v106, vcc, 0xb9f0000, v104
	s_nop 1
	v_addc_co_u32_e32 v107, vcc, 0, v105, vcc
	v_add_co_u32_e32 v106, vcc, 0xba68000, v104
	s_nop 1
	v_addc_co_u32_e32 v107, vcc, 0, v105, vcc
	v_add_co_u32_e32 v106, vcc, 0xbae0000, v104
	s_nop 1
	v_addc_co_u32_e32 v107, vcc, 0, v105, vcc
	v_add_co_u32_e32 v106, vcc, 0xbb58000, v104
	s_nop 1
	v_addc_co_u32_e32 v107, vcc, 0, v105, vcc
	v_add_co_u32_e32 v106, vcc, 0xbbd0000, v104
	s_nop 1
	v_addc_co_u32_e32 v107, vcc, 0, v105, vcc
	v_add_co_u32_e32 v104, vcc, 0xbc48000, v104
	s_nop 0
	v_addc_co_u32_e32 v105, vcc, 0, v105, vcc
.LBB0_539:
	s_or_b64 exec, exec, s[58:59]
	v_or_b32_e32 v104, 32, v128
	v_lshlrev_b32_e32 v106, 1, v104
	v_cvt_pk_bf16_f32 v104, v100, v101
	v_cvt_pk_bf16_f32 v105, v102, v103
	s_and_saveexec_b64 s[58:59], s[44:45]
	s_xor_b64 s[58:59], exec, s[58:59]
	s_cbranch_execz .LBB0_541
	v_lshlrev_b32_e32 v108, 2, v128
	v_mov_b32_e32 v109, v177
	v_lshl_add_u64 v[108:109], v[114:115], 0, v[108:109]
	v_mov_b32_e32 v107, v177
	global_store_dwordx4 v[108:109], v[100:103], off offset:128
	s_nop 1
	v_lshl_add_u64 v[100:101], v[112:113], 0, v[106:107]
	v_add_co_u32_e32 v102, vcc, 0x5100000, v100
	s_nop 1
	v_addc_co_u32_e32 v103, vcc, 0, v101, vcc
	global_store_dwordx2 v[102:103], v[104:105], off offset:256
	v_add_co_u32_e32 v102, vcc, 0x5118000, v100
	s_nop 1
	v_addc_co_u32_e32 v103, vcc, 0, v101, vcc
	v_add_co_u32_e32 v102, vcc, 0x5130000, v100
	s_nop 1
	v_addc_co_u32_e32 v103, vcc, 0, v101, vcc
	v_add_co_u32_e32 v102, vcc, 0x5148000, v100
	s_nop 1
	v_addc_co_u32_e32 v103, vcc, 0, v101, vcc
	v_add_co_u32_e32 v102, vcc, 0x5160000, v100
	s_nop 1
	v_addc_co_u32_e32 v103, vcc, 0, v101, vcc
	v_add_co_u32_e32 v102, vcc, 0x5178000, v100
	s_nop 1
	v_addc_co_u32_e32 v103, vcc, 0, v101, vcc
	v_add_co_u32_e32 v102, vcc, 0x5190000, v100
	s_nop 1
	v_addc_co_u32_e32 v103, vcc, 0, v101, vcc
	v_add_co_u32_e32 v100, vcc, 0x51a8000, v100
	s_nop 0
	v_addc_co_u32_e32 v101, vcc, 0, v101, vcc
.LBB0_541:
	s_andn2_saveexec_b64 s[58:59], s[58:59]
	s_cbranch_execz .LBB0_543
	v_mov_b32_e32 v107, v177
	v_lshl_add_u64 v[100:101], v[116:117], 0, v[106:107]
	v_add_co_u32_e32 v102, vcc, 0xb900000, v100
	s_nop 1
	v_addc_co_u32_e32 v103, vcc, 0, v101, vcc
	global_store_dwordx2 v[102:103], v[104:105], off offset:256
	v_add_co_u32_e32 v102, vcc, 0xb978000, v100
	s_nop 1
	v_addc_co_u32_e32 v103, vcc, 0, v101, vcc
	v_add_co_u32_e32 v102, vcc, 0xb9f0000, v100
	s_nop 1
	v_addc_co_u32_e32 v103, vcc, 0, v101, vcc
	v_add_co_u32_e32 v102, vcc, 0xba68000, v100
	s_nop 1
	v_addc_co_u32_e32 v103, vcc, 0, v101, vcc
	v_add_co_u32_e32 v102, vcc, 0xbae0000, v100
	s_nop 1
	v_addc_co_u32_e32 v103, vcc, 0, v101, vcc
	v_add_co_u32_e32 v102, vcc, 0xbb58000, v100
	s_nop 1
	v_addc_co_u32_e32 v103, vcc, 0, v101, vcc
	v_add_co_u32_e32 v102, vcc, 0xbbd0000, v100
	s_nop 1
	v_addc_co_u32_e32 v103, vcc, 0, v101, vcc
	v_add_co_u32_e32 v100, vcc, 0xbc48000, v100
	s_nop 0
	v_addc_co_u32_e32 v101, vcc, 0, v101, vcc
.LBB0_543:
	s_or_b64 exec, exec, s[58:59]
	v_or_b32_e32 v100, 48, v128
	v_lshlrev_b32_e32 v102, 1, v100
	v_cvt_pk_bf16_f32 v100, v96, v97
	v_cvt_pk_bf16_f32 v101, v98, v99
	s_and_saveexec_b64 s[58:59], s[44:45]
	s_xor_b64 s[58:59], exec, s[58:59]
	s_cbranch_execz .LBB0_545
	v_lshlrev_b32_e32 v104, 2, v128
	v_mov_b32_e32 v105, v177
	v_lshl_add_u64 v[104:105], v[114:115], 0, v[104:105]
	v_mov_b32_e32 v103, v177
	global_store_dwordx4 v[104:105], v[96:99], off offset:192
	s_nop 1
	v_lshl_add_u64 v[96:97], v[112:113], 0, v[102:103]
	v_add_co_u32_e32 v98, vcc, 0x5100000, v96
	s_nop 1
	v_addc_co_u32_e32 v99, vcc, 0, v97, vcc
	global_store_dwordx2 v[98:99], v[100:101], off offset:256
	v_add_co_u32_e32 v98, vcc, 0x5118000, v96
	s_nop 1
	v_addc_co_u32_e32 v99, vcc, 0, v97, vcc
	v_add_co_u32_e32 v98, vcc, 0x5130000, v96
	s_nop 1
	v_addc_co_u32_e32 v99, vcc, 0, v97, vcc
	v_add_co_u32_e32 v98, vcc, 0x5148000, v96
	s_nop 1
	v_addc_co_u32_e32 v99, vcc, 0, v97, vcc
	v_add_co_u32_e32 v98, vcc, 0x5160000, v96
	s_nop 1
	v_addc_co_u32_e32 v99, vcc, 0, v97, vcc
	v_add_co_u32_e32 v98, vcc, 0x5178000, v96
	s_nop 1
	v_addc_co_u32_e32 v99, vcc, 0, v97, vcc
	v_add_co_u32_e32 v98, vcc, 0x5190000, v96
	s_nop 1
	v_addc_co_u32_e32 v99, vcc, 0, v97, vcc
	v_add_co_u32_e32 v96, vcc, 0x51a8000, v96
	s_nop 0
	v_addc_co_u32_e32 v97, vcc, 0, v97, vcc
.LBB0_545:
	s_andn2_saveexec_b64 s[58:59], s[58:59]
	s_cbranch_execz .LBB0_547
	v_mov_b32_e32 v103, v177
	v_lshl_add_u64 v[96:97], v[116:117], 0, v[102:103]
	v_add_co_u32_e32 v98, vcc, 0xb900000, v96
	s_nop 1
	v_addc_co_u32_e32 v99, vcc, 0, v97, vcc
	global_store_dwordx2 v[98:99], v[100:101], off offset:256
	v_add_co_u32_e32 v98, vcc, 0xb978000, v96
	s_nop 1
	v_addc_co_u32_e32 v99, vcc, 0, v97, vcc
	v_add_co_u32_e32 v98, vcc, 0xb9f0000, v96
	s_nop 1
	v_addc_co_u32_e32 v99, vcc, 0, v97, vcc
	v_add_co_u32_e32 v98, vcc, 0xba68000, v96
	s_nop 1
	v_addc_co_u32_e32 v99, vcc, 0, v97, vcc
	v_add_co_u32_e32 v98, vcc, 0xbae0000, v96
	s_nop 1
	v_addc_co_u32_e32 v99, vcc, 0, v97, vcc
	v_add_co_u32_e32 v98, vcc, 0xbb58000, v96
	s_nop 1
	v_addc_co_u32_e32 v99, vcc, 0, v97, vcc
	v_add_co_u32_e32 v98, vcc, 0xbbd0000, v96
	s_nop 1
	v_addc_co_u32_e32 v99, vcc, 0, v97, vcc
	v_add_co_u32_e32 v96, vcc, 0xbc48000, v96
	s_nop 0
	v_addc_co_u32_e32 v97, vcc, 0, v97, vcc

.LBB0_571:
	s_or_b64 exec, exec, vcc
	v_lshlrev_b32_e32 v144, 1, v128
	v_mov_b32_e32 v145, v177
	v_lshl_add_u64 v[108:109], v[108:109], 0, v[144:145]
	v_cvt_pk_bf16_f32 v92, v92, v93
	v_cvt_pk_bf16_f32 v93, v94, v95
	v_lshl_add_u64 v[94:95], v[108:109], 0, v[142:143]
	v_lshl_add_u64 v[94:95], v[108:109], 0, v[140:141]
	v_lshl_add_u64 v[94:95], v[108:109], 0, v[126:127]
	v_lshl_add_u64 v[94:95], v[108:109], 0, v[124:125]
	v_lshl_add_u64 v[94:95], v[108:109], 0, v[122:123]
	v_lshl_add_u64 v[94:95], v[108:109], 0, v[120:121]
	v_lshl_add_u64 v[94:95], v[108:109], 0, v[118:119]
	v_lshl_add_u64 v[94:95], v[108:109], 0, v[116:117]
	v_lshl_add_u64 v[94:95], v[108:109], 0, v[114:115]
	v_lshl_add_u64 v[94:95], v[108:109], 0, v[112:113]
	v_lshl_add_u64 v[94:95], v[108:109], 0, v[110:111]
	v_lshl_add_u64 v[94:95], v[108:109], 0, v[106:107]
	v_lshl_add_u64 v[94:95], v[108:109], 0, v[104:105]
	global_store_dwordx2 v[108:109], v[92:93], off
	v_lshl_add_u64 v[94:95], v[108:109], 0, v[102:103]
	v_or_b32_e32 v92, 16, v128
	v_lshlrev_b32_e32 v94, 1, v92
	v_cvt_pk_bf16_f32 v92, v88, v89
	v_cvt_pk_bf16_f32 v93, v90, v91
	s_and_saveexec_b64 s[58:59], s[44:45]
	s_xor_b64 s[58:59], exec, s[58:59]
	s_cbranch_execz .LBB0_573
	v_lshlrev_b32_e32 v102, 2, v128
	v_mov_b32_e32 v103, v177
	v_lshl_add_u64 v[102:103], v[98:99], 0, v[102:103]
	v_mov_b32_e32 v95, v177
	global_store_dwordx4 v[102:103], v[88:91], off offset:64
	s_nop 1
	v_lshl_add_u64 v[88:89], v[96:97], 0, v[94:95]
	v_add_co_u32_e32 v90, vcc, 0x5100000, v88
	s_nop 1
	v_addc_co_u32_e32 v91, vcc, 0, v89, vcc
	global_store_dwordx2 v[90:91], v[92:93], off offset:256
	v_add_co_u32_e32 v90, vcc, 0x5118000, v88
	s_nop 1
	v_addc_co_u32_e32 v91, vcc, 0, v89, vcc
	v_add_co_u32_e32 v90, vcc, 0x5130000, v88
	s_nop 1
	v_addc_co_u32_e32 v91, vcc, 0, v89, vcc
	v_add_co_u32_e32 v90, vcc, 0x5148000, v88
	s_nop 1
	v_addc_co_u32_e32 v91, vcc, 0, v89, vcc
	v_add_co_u32_e32 v90, vcc, 0x5160000, v88
	s_nop 1
	v_addc_co_u32_e32 v91, vcc, 0, v89, vcc
	v_add_co_u32_e32 v90, vcc, 0x5178000, v88
	s_nop 1
	v_addc_co_u32_e32 v91, vcc, 0, v89, vcc
	v_add_co_u32_e32 v90, vcc, 0x5190000, v88
	s_nop 1
	v_addc_co_u32_e32 v91, vcc, 0, v89, vcc
	v_add_co_u32_e32 v88, vcc, 0x51a8000, v88
	s_nop 0
	v_addc_co_u32_e32 v89, vcc, 0, v89, vcc
.LBB0_573:
	s_andn2_saveexec_b64 s[58:59], s[58:59]
	s_cbranch_execz .LBB0_575
	v_mov_b32_e32 v95, v177
	v_lshl_add_u64 v[88:89], v[100:101], 0, v[94:95]
	v_add_co_u32_e32 v90, vcc, 0xb900000, v88
	s_nop 1
	v_addc_co_u32_e32 v91, vcc, 0, v89, vcc
	global_store_dwordx2 v[90:91], v[92:93], off offset:256
	v_add_co_u32_e32 v90, vcc, 0xb978000, v88
	s_nop 1
	v_addc_co_u32_e32 v91, vcc, 0, v89, vcc
	v_add_co_u32_e32 v90, vcc, 0xb9f0000, v88
	s_nop 1
	v_addc_co_u32_e32 v91, vcc, 0, v89, vcc
	v_add_co_u32_e32 v90, vcc, 0xba68000, v88
	s_nop 1
	v_addc_co_u32_e32 v91, vcc, 0, v89, vcc
	v_add_co_u32_e32 v90, vcc, 0xbae0000, v88
	s_nop 1
	v_addc_co_u32_e32 v91, vcc, 0, v89, vcc
	v_add_co_u32_e32 v90, vcc, 0xbb58000, v88
	s_nop 1
	v_addc_co_u32_e32 v91, vcc, 0, v89, vcc
	v_add_co_u32_e32 v90, vcc, 0xbbd0000, v88
	s_nop 1
	v_addc_co_u32_e32 v91, vcc, 0, v89, vcc
	v_add_co_u32_e32 v88, vcc, 0xbc48000, v88
	s_nop 0
	v_addc_co_u32_e32 v89, vcc, 0, v89, vcc
.LBB0_575:
	s_or_b64 exec, exec, s[58:59]
	v_or_b32_e32 v88, 32, v128
	v_lshlrev_b32_e32 v90, 1, v88
	v_cvt_pk_bf16_f32 v88, v84, v85
	v_cvt_pk_bf16_f32 v89, v86, v87
	s_and_saveexec_b64 s[58:59], s[44:45]
	s_xor_b64 s[58:59], exec, s[58:59]
	s_cbranch_execz .LBB0_577
	v_lshlrev_b32_e32 v92, 2, v128
	v_mov_b32_e32 v93, v177
	v_lshl_add_u64 v[92:93], v[98:99], 0, v[92:93]
	v_mov_b32_e32 v91, v177
	global_store_dwordx4 v[92:93], v[84:87], off offset:128
	s_nop 1
	v_lshl_add_u64 v[84:85], v[96:97], 0, v[90:91]
	v_add_co_u32_e32 v86, vcc, 0x5100000, v84
	s_nop 1
	v_addc_co_u32_e32 v87, vcc, 0, v85, vcc
	global_store_dwordx2 v[86:87], v[88:89], off offset:256
	v_add_co_u32_e32 v86, vcc, 0x5118000, v84
	s_nop 1
	v_addc_co_u32_e32 v87, vcc, 0, v85, vcc
	v_add_co_u32_e32 v86, vcc, 0x5130000, v84
	s_nop 1
	v_addc_co_u32_e32 v87, vcc, 0, v85, vcc
	v_add_co_u32_e32 v86, vcc, 0x5148000, v84
	s_nop 1
	v_addc_co_u32_e32 v87, vcc, 0, v85, vcc
	v_add_co_u32_e32 v86, vcc, 0x5160000, v84
	s_nop 1
	v_addc_co_u32_e32 v87, vcc, 0, v85, vcc
	v_add_co_u32_e32 v86, vcc, 0x5178000, v84
	s_nop 1
	v_addc_co_u32_e32 v87, vcc, 0, v85, vcc
	v_add_co_u32_e32 v86, vcc, 0x5190000, v84
	s_nop 1
	v_addc_co_u32_e32 v87, vcc, 0, v85, vcc
	v_add_co_u32_e32 v84, vcc, 0x51a8000, v84
	s_nop 0
	v_addc_co_u32_e32 v85, vcc, 0, v85, vcc
.LBB0_577:
	s_andn2_saveexec_b64 s[58:59], s[58:59]
	s_cbranch_execz .LBB0_579
	v_mov_b32_e32 v91, v177
	v_lshl_add_u64 v[84:85], v[100:101], 0, v[90:91]
	v_add_co_u32_e32 v86, vcc, 0xb900000, v84
	s_nop 1
	v_addc_co_u32_e32 v87, vcc, 0, v85, vcc
	global_store_dwordx2 v[86:87], v[88:89], off offset:256
	v_add_co_u32_e32 v86, vcc, 0xb978000, v84
	s_nop 1
	v_addc_co_u32_e32 v87, vcc, 0, v85, vcc
	v_add_co_u32_e32 v86, vcc, 0xb9f0000, v84
	s_nop 1
	v_addc_co_u32_e32 v87, vcc, 0, v85, vcc
	v_add_co_u32_e32 v86, vcc, 0xba68000, v84
	s_nop 1
	v_addc_co_u32_e32 v87, vcc, 0, v85, vcc
	v_add_co_u32_e32 v86, vcc, 0xbae0000, v84
	s_nop 1
	v_addc_co_u32_e32 v87, vcc, 0, v85, vcc
	v_add_co_u32_e32 v86, vcc, 0xbb58000, v84
	s_nop 1
	v_addc_co_u32_e32 v87, vcc, 0, v85, vcc
	v_add_co_u32_e32 v86, vcc, 0xbbd0000, v84
	s_nop 1
	v_addc_co_u32_e32 v87, vcc, 0, v85, vcc
	v_add_co_u32_e32 v84, vcc, 0xbc48000, v84
	s_nop 0
	v_addc_co_u32_e32 v85, vcc, 0, v85, vcc
.LBB0_579:
	s_or_b64 exec, exec, s[58:59]
	v_or_b32_e32 v84, 48, v128
	v_lshlrev_b32_e32 v86, 1, v84
	v_cvt_pk_bf16_f32 v84, v80, v81
	v_cvt_pk_bf16_f32 v85, v82, v83
	s_and_saveexec_b64 s[58:59], s[44:45]
	s_xor_b64 s[58:59], exec, s[58:59]
	s_cbranch_execz .LBB0_581
	v_lshlrev_b32_e32 v88, 2, v128
	v_mov_b32_e32 v89, v177
	v_lshl_add_u64 v[88:89], v[98:99], 0, v[88:89]
	v_mov_b32_e32 v87, v177
	global_store_dwordx4 v[88:89], v[80:83], off offset:192
	s_nop 1
	v_lshl_add_u64 v[80:81], v[96:97], 0, v[86:87]
	v_add_co_u32_e32 v82, vcc, 0x5100000, v80
	s_nop 1
	v_addc_co_u32_e32 v83, vcc, 0, v81, vcc
	global_store_dwordx2 v[82:83], v[84:85], off offset:256
	v_add_co_u32_e32 v82, vcc, 0x5118000, v80
	s_nop 1
	v_addc_co_u32_e32 v83, vcc, 0, v81, vcc
	v_add_co_u32_e32 v82, vcc, 0x5130000, v80
	s_nop 1
	v_addc_co_u32_e32 v83, vcc, 0, v81, vcc
	v_add_co_u32_e32 v82, vcc, 0x5148000, v80
	s_nop 1
	v_addc_co_u32_e32 v83, vcc, 0, v81, vcc
	v_add_co_u32_e32 v82, vcc, 0x5160000, v80
	s_nop 1
	v_addc_co_u32_e32 v83, vcc, 0, v81, vcc
	v_add_co_u32_e32 v82, vcc, 0x5178000, v80
	s_nop 1
	v_addc_co_u32_e32 v83, vcc, 0, v81, vcc
	v_add_co_u32_e32 v82, vcc, 0x5190000, v80
	s_nop 1
	v_addc_co_u32_e32 v83, vcc, 0, v81, vcc
	v_add_co_u32_e32 v80, vcc, 0x51a8000, v80
	s_nop 0
	v_addc_co_u32_e32 v81, vcc, 0, v81, vcc
.LBB0_581:
	s_andn2_saveexec_b64 s[58:59], s[58:59]
	s_cbranch_execz .LBB0_583
	v_mov_b32_e32 v87, v177
	v_lshl_add_u64 v[80:81], v[100:101], 0, v[86:87]
	v_add_co_u32_e32 v82, vcc, 0xb900000, v80
	s_nop 1
	v_addc_co_u32_e32 v83, vcc, 0, v81, vcc
	global_store_dwordx2 v[82:83], v[84:85], off offset:256
	v_add_co_u32_e32 v82, vcc, 0xb978000, v80
	s_nop 1
	v_addc_co_u32_e32 v83, vcc, 0, v81, vcc
	v_add_co_u32_e32 v82, vcc, 0xb9f0000, v80
	s_nop 1
	v_addc_co_u32_e32 v83, vcc, 0, v81, vcc
	v_add_co_u32_e32 v82, vcc, 0xba68000, v80
	s_nop 1
	v_addc_co_u32_e32 v83, vcc, 0, v81, vcc
	v_add_co_u32_e32 v82, vcc, 0xbae0000, v80
	s_nop 1
	v_addc_co_u32_e32 v83, vcc, 0, v81, vcc
	v_add_co_u32_e32 v82, vcc, 0xbb58000, v80
	s_nop 1
	v_addc_co_u32_e32 v83, vcc, 0, v81, vcc
	v_add_co_u32_e32 v82, vcc, 0xbbd0000, v80
	s_nop 1
	v_addc_co_u32_e32 v83, vcc, 0, v81, vcc
	v_add_co_u32_e32 v80, vcc, 0xbc48000, v80
	s_nop 0
	v_addc_co_u32_e32 v81, vcc, 0, v81, vcc

.LBB0_607:
	s_or_b64 exec, exec, vcc
	v_lshlrev_b32_e32 v116, 1, v128
	v_mov_b32_e32 v117, v177
	v_lshl_add_u64 v[92:93], v[92:93], 0, v[116:117]
	v_cvt_pk_bf16_f32 v76, v76, v77
	v_cvt_pk_bf16_f32 v77, v78, v79
	v_lshl_add_u64 v[78:79], v[92:93], 0, v[114:115]
	v_lshl_add_u64 v[78:79], v[92:93], 0, v[112:113]
	v_lshl_add_u64 v[78:79], v[92:93], 0, v[110:111]
	v_lshl_add_u64 v[78:79], v[92:93], 0, v[108:109]
	v_lshl_add_u64 v[78:79], v[92:93], 0, v[106:107]
	v_lshl_add_u64 v[78:79], v[92:93], 0, v[104:105]
	v_lshl_add_u64 v[78:79], v[92:93], 0, v[102:103]
	v_lshl_add_u64 v[78:79], v[92:93], 0, v[100:101]
	v_lshl_add_u64 v[78:79], v[92:93], 0, v[98:99]
	v_lshl_add_u64 v[78:79], v[92:93], 0, v[96:97]
	v_lshl_add_u64 v[78:79], v[92:93], 0, v[94:95]
	v_lshl_add_u64 v[78:79], v[92:93], 0, v[90:91]
	v_lshl_add_u64 v[78:79], v[92:93], 0, v[88:89]
	global_store_dwordx2 v[92:93], v[76:77], off
	v_lshl_add_u64 v[78:79], v[92:93], 0, v[86:87]
	v_or_b32_e32 v76, 16, v128
	v_lshlrev_b32_e32 v78, 1, v76
	v_cvt_pk_bf16_f32 v76, v72, v73
	v_cvt_pk_bf16_f32 v77, v74, v75
	s_and_saveexec_b64 s[58:59], s[44:45]
	s_xor_b64 s[58:59], exec, s[58:59]
	s_cbranch_execz .LBB0_609
	v_lshlrev_b32_e32 v86, 2, v128
	v_mov_b32_e32 v87, v177
	v_lshl_add_u64 v[86:87], v[82:83], 0, v[86:87]
	v_mov_b32_e32 v79, v177
	global_store_dwordx4 v[86:87], v[72:75], off offset:64
	s_nop 1
	v_lshl_add_u64 v[72:73], v[80:81], 0, v[78:79]
	v_add_co_u32_e32 v74, vcc, 0x5100000, v72
	s_nop 1
	v_addc_co_u32_e32 v75, vcc, 0, v73, vcc
	global_store_dwordx2 v[74:75], v[76:77], off offset:256
	v_add_co_u32_e32 v74, vcc, 0x5118000, v72
	s_nop 1
	v_addc_co_u32_e32 v75, vcc, 0, v73, vcc
	v_add_co_u32_e32 v74, vcc, 0x5130000, v72
	s_nop 1
	v_addc_co_u32_e32 v75, vcc, 0, v73, vcc
	v_add_co_u32_e32 v74, vcc, 0x5148000, v72
	s_nop 1
	v_addc_co_u32_e32 v75, vcc, 0, v73, vcc
	v_add_co_u32_e32 v74, vcc, 0x5160000, v72
	s_nop 1
	v_addc_co_u32_e32 v75, vcc, 0, v73, vcc
	v_add_co_u32_e32 v74, vcc, 0x5178000, v72
	s_nop 1
	v_addc_co_u32_e32 v75, vcc, 0, v73, vcc
	v_add_co_u32_e32 v74, vcc, 0x5190000, v72
	s_nop 1
	v_addc_co_u32_e32 v75, vcc, 0, v73, vcc
	v_add_co_u32_e32 v72, vcc, 0x51a8000, v72
	s_nop 0
	v_addc_co_u32_e32 v73, vcc, 0, v73, vcc
.LBB0_609:
	s_andn2_saveexec_b64 s[58:59], s[58:59]
	s_cbranch_execz .LBB0_611
	v_mov_b32_e32 v79, v177
	v_lshl_add_u64 v[72:73], v[84:85], 0, v[78:79]
	v_add_co_u32_e32 v74, vcc, 0xb900000, v72
	s_nop 1
	v_addc_co_u32_e32 v75, vcc, 0, v73, vcc
	global_store_dwordx2 v[74:75], v[76:77], off offset:256
	v_add_co_u32_e32 v74, vcc, 0xb978000, v72
	s_nop 1
	v_addc_co_u32_e32 v75, vcc, 0, v73, vcc
	v_add_co_u32_e32 v74, vcc, 0xb9f0000, v72
	s_nop 1
	v_addc_co_u32_e32 v75, vcc, 0, v73, vcc
	v_add_co_u32_e32 v74, vcc, 0xba68000, v72
	s_nop 1
	v_addc_co_u32_e32 v75, vcc, 0, v73, vcc
	v_add_co_u32_e32 v74, vcc, 0xbae0000, v72
	s_nop 1
	v_addc_co_u32_e32 v75, vcc, 0, v73, vcc
	v_add_co_u32_e32 v74, vcc, 0xbb58000, v72
	s_nop 1
	v_addc_co_u32_e32 v75, vcc, 0, v73, vcc
	v_add_co_u32_e32 v74, vcc, 0xbbd0000, v72
	s_nop 1
	v_addc_co_u32_e32 v75, vcc, 0, v73, vcc
	v_add_co_u32_e32 v72, vcc, 0xbc48000, v72
	s_nop 0
	v_addc_co_u32_e32 v73, vcc, 0, v73, vcc
.LBB0_611:
	s_or_b64 exec, exec, s[58:59]
	v_or_b32_e32 v72, 32, v128
	v_lshlrev_b32_e32 v74, 1, v72
	v_cvt_pk_bf16_f32 v72, v68, v69
	v_cvt_pk_bf16_f32 v73, v70, v71
	s_and_saveexec_b64 s[58:59], s[44:45]
	s_xor_b64 s[58:59], exec, s[58:59]
	s_cbranch_execz .LBB0_613
	v_lshlrev_b32_e32 v76, 2, v128
	v_mov_b32_e32 v77, v177
	v_lshl_add_u64 v[76:77], v[82:83], 0, v[76:77]
	v_mov_b32_e32 v75, v177
	global_store_dwordx4 v[76:77], v[68:71], off offset:128
	s_nop 1
	v_lshl_add_u64 v[68:69], v[80:81], 0, v[74:75]
	v_add_co_u32_e32 v70, vcc, 0x5100000, v68
	s_nop 1
	v_addc_co_u32_e32 v71, vcc, 0, v69, vcc
	global_store_dwordx2 v[70:71], v[72:73], off offset:256
	v_add_co_u32_e32 v70, vcc, 0x5118000, v68
	s_nop 1
	v_addc_co_u32_e32 v71, vcc, 0, v69, vcc
	v_add_co_u32_e32 v70, vcc, 0x5130000, v68
	s_nop 1
	v_addc_co_u32_e32 v71, vcc, 0, v69, vcc
	v_add_co_u32_e32 v70, vcc, 0x5148000, v68
	s_nop 1
	v_addc_co_u32_e32 v71, vcc, 0, v69, vcc
	v_add_co_u32_e32 v70, vcc, 0x5160000, v68
	s_nop 1
	v_addc_co_u32_e32 v71, vcc, 0, v69, vcc
	v_add_co_u32_e32 v70, vcc, 0x5178000, v68
	s_nop 1
	v_addc_co_u32_e32 v71, vcc, 0, v69, vcc
	v_add_co_u32_e32 v70, vcc, 0x5190000, v68
	s_nop 1
	v_addc_co_u32_e32 v71, vcc, 0, v69, vcc
	v_add_co_u32_e32 v68, vcc, 0x51a8000, v68
	s_nop 0
	v_addc_co_u32_e32 v69, vcc, 0, v69, vcc
.LBB0_613:
	s_andn2_saveexec_b64 s[58:59], s[58:59]
	s_cbranch_execz .LBB0_615
	v_mov_b32_e32 v75, v177
	v_lshl_add_u64 v[68:69], v[84:85], 0, v[74:75]
	v_add_co_u32_e32 v70, vcc, 0xb900000, v68
	s_nop 1
	v_addc_co_u32_e32 v71, vcc, 0, v69, vcc
	global_store_dwordx2 v[70:71], v[72:73], off offset:256
	v_add_co_u32_e32 v70, vcc, 0xb978000, v68
	s_nop 1
	v_addc_co_u32_e32 v71, vcc, 0, v69, vcc
	v_add_co_u32_e32 v70, vcc, 0xb9f0000, v68
	s_nop 1
	v_addc_co_u32_e32 v71, vcc, 0, v69, vcc
	v_add_co_u32_e32 v70, vcc, 0xba68000, v68
	s_nop 1
	v_addc_co_u32_e32 v71, vcc, 0, v69, vcc
	v_add_co_u32_e32 v70, vcc, 0xbae0000, v68
	s_nop 1
	v_addc_co_u32_e32 v71, vcc, 0, v69, vcc
	v_add_co_u32_e32 v70, vcc, 0xbb58000, v68
	s_nop 1
	v_addc_co_u32_e32 v71, vcc, 0, v69, vcc
	v_add_co_u32_e32 v70, vcc, 0xbbd0000, v68
	s_nop 1
	v_addc_co_u32_e32 v71, vcc, 0, v69, vcc
	v_add_co_u32_e32 v68, vcc, 0xbc48000, v68
	s_nop 0
	v_addc_co_u32_e32 v69, vcc, 0, v69, vcc
.LBB0_615:
	s_or_b64 exec, exec, s[58:59]
	v_or_b32_e32 v68, 48, v128
	v_lshlrev_b32_e32 v70, 1, v68
	v_cvt_pk_bf16_f32 v68, v64, v65
	v_cvt_pk_bf16_f32 v69, v66, v67
	s_and_saveexec_b64 s[58:59], s[44:45]
	s_xor_b64 s[58:59], exec, s[58:59]
	s_cbranch_execz .LBB0_617
	v_lshlrev_b32_e32 v72, 2, v128
	v_mov_b32_e32 v73, v177
	v_lshl_add_u64 v[72:73], v[82:83], 0, v[72:73]
	v_mov_b32_e32 v71, v177
	global_store_dwordx4 v[72:73], v[64:67], off offset:192
	s_nop 1
	v_lshl_add_u64 v[64:65], v[80:81], 0, v[70:71]
	v_add_co_u32_e32 v66, vcc, 0x5100000, v64
	s_nop 1
	v_addc_co_u32_e32 v67, vcc, 0, v65, vcc
	global_store_dwordx2 v[66:67], v[68:69], off offset:256
	v_add_co_u32_e32 v66, vcc, 0x5118000, v64
	s_nop 1
	v_addc_co_u32_e32 v67, vcc, 0, v65, vcc
	v_add_co_u32_e32 v66, vcc, 0x5130000, v64
	s_nop 1
	v_addc_co_u32_e32 v67, vcc, 0, v65, vcc
	v_add_co_u32_e32 v66, vcc, 0x5148000, v64
	s_nop 1
	v_addc_co_u32_e32 v67, vcc, 0, v65, vcc
	v_add_co_u32_e32 v66, vcc, 0x5160000, v64
	s_nop 1
	v_addc_co_u32_e32 v67, vcc, 0, v65, vcc
	v_add_co_u32_e32 v66, vcc, 0x5178000, v64
	s_nop 1
	v_addc_co_u32_e32 v67, vcc, 0, v65, vcc
	v_add_co_u32_e32 v66, vcc, 0x5190000, v64
	s_nop 1
	v_addc_co_u32_e32 v67, vcc, 0, v65, vcc
	v_add_co_u32_e32 v64, vcc, 0x51a8000, v64
	s_nop 0
	v_addc_co_u32_e32 v65, vcc, 0, v65, vcc
.LBB0_617:
	s_andn2_saveexec_b64 s[58:59], s[58:59]
	s_cbranch_execz .LBB0_619
	v_mov_b32_e32 v71, v177
	v_lshl_add_u64 v[64:65], v[84:85], 0, v[70:71]
	v_add_co_u32_e32 v66, vcc, 0xb900000, v64
	s_nop 1
	v_addc_co_u32_e32 v67, vcc, 0, v65, vcc
	global_store_dwordx2 v[66:67], v[68:69], off offset:256
	v_add_co_u32_e32 v66, vcc, 0xb978000, v64
	s_nop 1
	v_addc_co_u32_e32 v67, vcc, 0, v65, vcc
	v_add_co_u32_e32 v66, vcc, 0xb9f0000, v64
	s_nop 1
	v_addc_co_u32_e32 v67, vcc, 0, v65, vcc
	v_add_co_u32_e32 v66, vcc, 0xba68000, v64
	s_nop 1
	v_addc_co_u32_e32 v67, vcc, 0, v65, vcc
	v_add_co_u32_e32 v66, vcc, 0xbae0000, v64
	s_nop 1
	v_addc_co_u32_e32 v67, vcc, 0, v65, vcc
	v_add_co_u32_e32 v66, vcc, 0xbb58000, v64
	s_nop 1
	v_addc_co_u32_e32 v67, vcc, 0, v65, vcc
	v_add_co_u32_e32 v66, vcc, 0xbbd0000, v64
	s_nop 1
	v_addc_co_u32_e32 v67, vcc, 0, v65, vcc
	v_add_co_u32_e32 v64, vcc, 0xbc48000, v64
	s_nop 0
	v_addc_co_u32_e32 v65, vcc, 0, v65, vcc

.LBB0_643:
	s_or_b64 exec, exec, vcc
	v_lshlrev_b32_e32 v100, 1, v128
	v_mov_b32_e32 v101, v177
	v_lshl_add_u64 v[76:77], v[76:77], 0, v[100:101]
	v_cvt_pk_bf16_f32 v60, v60, v61
	v_cvt_pk_bf16_f32 v61, v62, v63
	v_lshl_add_u64 v[62:63], v[76:77], 0, v[98:99]
	v_lshl_add_u64 v[62:63], v[76:77], 0, v[96:97]
	v_lshl_add_u64 v[62:63], v[76:77], 0, v[94:95]
	v_lshl_add_u64 v[62:63], v[76:77], 0, v[92:93]
	v_lshl_add_u64 v[62:63], v[76:77], 0, v[90:91]
	v_lshl_add_u64 v[62:63], v[76:77], 0, v[88:89]
	v_lshl_add_u64 v[62:63], v[76:77], 0, v[86:87]
	v_lshl_add_u64 v[62:63], v[76:77], 0, v[84:85]
	v_lshl_add_u64 v[62:63], v[76:77], 0, v[82:83]
	v_lshl_add_u64 v[62:63], v[76:77], 0, v[80:81]
	v_lshl_add_u64 v[62:63], v[76:77], 0, v[78:79]
	v_lshl_add_u64 v[62:63], v[76:77], 0, v[74:75]
	v_lshl_add_u64 v[62:63], v[76:77], 0, v[72:73]
	global_store_dwordx2 v[76:77], v[60:61], off
	v_lshl_add_u64 v[62:63], v[76:77], 0, v[70:71]
	v_or_b32_e32 v60, 16, v128
	v_lshlrev_b32_e32 v62, 1, v60
	v_cvt_pk_bf16_f32 v60, v56, v57
	v_cvt_pk_bf16_f32 v61, v58, v59
	s_and_saveexec_b64 s[58:59], s[44:45]
	s_xor_b64 s[58:59], exec, s[58:59]
	s_cbranch_execz .LBB0_645
	v_lshlrev_b32_e32 v70, 2, v128
	v_mov_b32_e32 v71, v177
	v_lshl_add_u64 v[70:71], v[66:67], 0, v[70:71]
	v_mov_b32_e32 v63, v177
	global_store_dwordx4 v[70:71], v[56:59], off offset:64
	s_nop 1
	v_lshl_add_u64 v[56:57], v[64:65], 0, v[62:63]
	v_add_co_u32_e32 v58, vcc, 0x5100000, v56
	s_nop 1
	v_addc_co_u32_e32 v59, vcc, 0, v57, vcc
	global_store_dwordx2 v[58:59], v[60:61], off offset:256
	v_add_co_u32_e32 v58, vcc, 0x5118000, v56
	s_nop 1
	v_addc_co_u32_e32 v59, vcc, 0, v57, vcc
	v_add_co_u32_e32 v58, vcc, 0x5130000, v56
	s_nop 1
	v_addc_co_u32_e32 v59, vcc, 0, v57, vcc
	v_add_co_u32_e32 v58, vcc, 0x5148000, v56
	s_nop 1
	v_addc_co_u32_e32 v59, vcc, 0, v57, vcc
	v_add_co_u32_e32 v58, vcc, 0x5160000, v56
	s_nop 1
	v_addc_co_u32_e32 v59, vcc, 0, v57, vcc
	v_add_co_u32_e32 v58, vcc, 0x5178000, v56
	s_nop 1
	v_addc_co_u32_e32 v59, vcc, 0, v57, vcc
	v_add_co_u32_e32 v58, vcc, 0x5190000, v56
	s_nop 1
	v_addc_co_u32_e32 v59, vcc, 0, v57, vcc
	v_add_co_u32_e32 v56, vcc, 0x51a8000, v56
	s_nop 0
	v_addc_co_u32_e32 v57, vcc, 0, v57, vcc
.LBB0_645:
	s_andn2_saveexec_b64 s[58:59], s[58:59]
	s_cbranch_execz .LBB0_647
	v_mov_b32_e32 v63, v177
	v_lshl_add_u64 v[56:57], v[68:69], 0, v[62:63]
	v_add_co_u32_e32 v58, vcc, 0xb900000, v56
	s_nop 1
	v_addc_co_u32_e32 v59, vcc, 0, v57, vcc
	global_store_dwordx2 v[58:59], v[60:61], off offset:256
	v_add_co_u32_e32 v58, vcc, 0xb978000, v56
	s_nop 1
	v_addc_co_u32_e32 v59, vcc, 0, v57, vcc
	v_add_co_u32_e32 v58, vcc, 0xb9f0000, v56
	s_nop 1
	v_addc_co_u32_e32 v59, vcc, 0, v57, vcc
	v_add_co_u32_e32 v58, vcc, 0xba68000, v56
	s_nop 1
	v_addc_co_u32_e32 v59, vcc, 0, v57, vcc
	v_add_co_u32_e32 v58, vcc, 0xbae0000, v56
	s_nop 1
	v_addc_co_u32_e32 v59, vcc, 0, v57, vcc
	v_add_co_u32_e32 v58, vcc, 0xbb58000, v56
	s_nop 1
	v_addc_co_u32_e32 v59, vcc, 0, v57, vcc
	v_add_co_u32_e32 v58, vcc, 0xbbd0000, v56
	s_nop 1
	v_addc_co_u32_e32 v59, vcc, 0, v57, vcc
	v_add_co_u32_e32 v56, vcc, 0xbc48000, v56
	s_nop 0
	v_addc_co_u32_e32 v57, vcc, 0, v57, vcc
.LBB0_647:
	s_or_b64 exec, exec, s[58:59]
	v_or_b32_e32 v56, 32, v128
	v_lshlrev_b32_e32 v58, 1, v56
	v_cvt_pk_bf16_f32 v56, v52, v53
	v_cvt_pk_bf16_f32 v57, v54, v55
	s_and_saveexec_b64 s[58:59], s[44:45]
	s_xor_b64 s[58:59], exec, s[58:59]
	s_cbranch_execz .LBB0_649
	v_lshlrev_b32_e32 v60, 2, v128
	v_mov_b32_e32 v61, v177
	v_lshl_add_u64 v[60:61], v[66:67], 0, v[60:61]
	v_mov_b32_e32 v59, v177
	global_store_dwordx4 v[60:61], v[52:55], off offset:128
	s_nop 1
	v_lshl_add_u64 v[52:53], v[64:65], 0, v[58:59]
	v_add_co_u32_e32 v54, vcc, 0x5100000, v52
	s_nop 1
	v_addc_co_u32_e32 v55, vcc, 0, v53, vcc
	global_store_dwordx2 v[54:55], v[56:57], off offset:256
	v_add_co_u32_e32 v54, vcc, 0x5118000, v52
	s_nop 1
	v_addc_co_u32_e32 v55, vcc, 0, v53, vcc
	v_add_co_u32_e32 v54, vcc, 0x5130000, v52
	s_nop 1
	v_addc_co_u32_e32 v55, vcc, 0, v53, vcc
	v_add_co_u32_e32 v54, vcc, 0x5148000, v52
	s_nop 1
	v_addc_co_u32_e32 v55, vcc, 0, v53, vcc
	v_add_co_u32_e32 v54, vcc, 0x5160000, v52
	s_nop 1
	v_addc_co_u32_e32 v55, vcc, 0, v53, vcc
	v_add_co_u32_e32 v54, vcc, 0x5178000, v52
	s_nop 1
	v_addc_co_u32_e32 v55, vcc, 0, v53, vcc
	v_add_co_u32_e32 v54, vcc, 0x5190000, v52
	s_nop 1
	v_addc_co_u32_e32 v55, vcc, 0, v53, vcc
	v_add_co_u32_e32 v52, vcc, 0x51a8000, v52
	s_nop 0
	v_addc_co_u32_e32 v53, vcc, 0, v53, vcc
.LBB0_649:
	s_andn2_saveexec_b64 s[58:59], s[58:59]
	s_cbranch_execz .LBB0_651
	v_mov_b32_e32 v59, v177
	v_lshl_add_u64 v[52:53], v[68:69], 0, v[58:59]
	v_add_co_u32_e32 v54, vcc, 0xb900000, v52
	s_nop 1
	v_addc_co_u32_e32 v55, vcc, 0, v53, vcc
	global_store_dwordx2 v[54:55], v[56:57], off offset:256
	v_add_co_u32_e32 v54, vcc, 0xb978000, v52
	s_nop 1
	v_addc_co_u32_e32 v55, vcc, 0, v53, vcc
	v_add_co_u32_e32 v54, vcc, 0xb9f0000, v52
	s_nop 1
	v_addc_co_u32_e32 v55, vcc, 0, v53, vcc
	v_add_co_u32_e32 v54, vcc, 0xba68000, v52
	s_nop 1
	v_addc_co_u32_e32 v55, vcc, 0, v53, vcc
	v_add_co_u32_e32 v54, vcc, 0xbae0000, v52
	s_nop 1
	v_addc_co_u32_e32 v55, vcc, 0, v53, vcc
	v_add_co_u32_e32 v54, vcc, 0xbb58000, v52
	s_nop 1
	v_addc_co_u32_e32 v55, vcc, 0, v53, vcc
	v_add_co_u32_e32 v54, vcc, 0xbbd0000, v52
	s_nop 1
	v_addc_co_u32_e32 v55, vcc, 0, v53, vcc
	v_add_co_u32_e32 v52, vcc, 0xbc48000, v52
	s_nop 0
	v_addc_co_u32_e32 v53, vcc, 0, v53, vcc
.LBB0_651:
	s_or_b64 exec, exec, s[58:59]
	v_or_b32_e32 v52, 48, v128
	v_lshlrev_b32_e32 v54, 1, v52
	v_cvt_pk_bf16_f32 v52, v48, v49
	v_cvt_pk_bf16_f32 v53, v50, v51
	s_and_saveexec_b64 s[58:59], s[44:45]
	s_xor_b64 s[58:59], exec, s[58:59]
	s_cbranch_execz .LBB0_653
	v_lshlrev_b32_e32 v56, 2, v128
	v_mov_b32_e32 v57, v177
	v_lshl_add_u64 v[56:57], v[66:67], 0, v[56:57]
	v_mov_b32_e32 v55, v177
	global_store_dwordx4 v[56:57], v[48:51], off offset:192
	s_nop 1
	v_lshl_add_u64 v[48:49], v[64:65], 0, v[54:55]
	v_add_co_u32_e32 v50, vcc, 0x5100000, v48
	s_nop 1
	v_addc_co_u32_e32 v51, vcc, 0, v49, vcc
	global_store_dwordx2 v[50:51], v[52:53], off offset:256
	v_add_co_u32_e32 v50, vcc, 0x5118000, v48
	s_nop 1
	v_addc_co_u32_e32 v51, vcc, 0, v49, vcc
	v_add_co_u32_e32 v50, vcc, 0x5130000, v48
	s_nop 1
	v_addc_co_u32_e32 v51, vcc, 0, v49, vcc
	v_add_co_u32_e32 v50, vcc, 0x5148000, v48
	s_nop 1
	v_addc_co_u32_e32 v51, vcc, 0, v49, vcc
	v_add_co_u32_e32 v50, vcc, 0x5160000, v48
	s_nop 1
	v_addc_co_u32_e32 v51, vcc, 0, v49, vcc
	v_add_co_u32_e32 v50, vcc, 0x5178000, v48
	s_nop 1
	v_addc_co_u32_e32 v51, vcc, 0, v49, vcc
	v_add_co_u32_e32 v50, vcc, 0x5190000, v48
	s_nop 1
	v_addc_co_u32_e32 v51, vcc, 0, v49, vcc
	v_add_co_u32_e32 v48, vcc, 0x51a8000, v48
	s_nop 0
	v_addc_co_u32_e32 v49, vcc, 0, v49, vcc
.LBB0_653:
	s_andn2_saveexec_b64 s[58:59], s[58:59]
	s_cbranch_execz .LBB0_655
	v_mov_b32_e32 v55, v177
	v_lshl_add_u64 v[48:49], v[68:69], 0, v[54:55]
	v_add_co_u32_e32 v50, vcc, 0xb900000, v48
	s_nop 1
	v_addc_co_u32_e32 v51, vcc, 0, v49, vcc
	global_store_dwordx2 v[50:51], v[52:53], off offset:256
	v_add_co_u32_e32 v50, vcc, 0xb978000, v48
	s_nop 1
	v_addc_co_u32_e32 v51, vcc, 0, v49, vcc
	v_add_co_u32_e32 v50, vcc, 0xb9f0000, v48
	s_nop 1
	v_addc_co_u32_e32 v51, vcc, 0, v49, vcc
	v_add_co_u32_e32 v50, vcc, 0xba68000, v48
	s_nop 1
	v_addc_co_u32_e32 v51, vcc, 0, v49, vcc
	v_add_co_u32_e32 v50, vcc, 0xbae0000, v48
	s_nop 1
	v_addc_co_u32_e32 v51, vcc, 0, v49, vcc
	v_add_co_u32_e32 v50, vcc, 0xbb58000, v48
	s_nop 1
	v_addc_co_u32_e32 v51, vcc, 0, v49, vcc
	v_add_co_u32_e32 v50, vcc, 0xbbd0000, v48
	s_nop 1
	v_addc_co_u32_e32 v51, vcc, 0, v49, vcc
	v_add_co_u32_e32 v48, vcc, 0xbc48000, v48
	s_nop 0
	v_addc_co_u32_e32 v49, vcc, 0, v49, vcc

.LBB0_679:
	s_or_b64 exec, exec, vcc
	v_lshlrev_b32_e32 v84, 1, v128
	v_mov_b32_e32 v85, v177
	v_lshl_add_u64 v[60:61], v[60:61], 0, v[84:85]
	v_cvt_pk_bf16_f32 v44, v44, v45
	v_cvt_pk_bf16_f32 v45, v46, v47
	v_lshl_add_u64 v[46:47], v[60:61], 0, v[82:83]
	v_lshl_add_u64 v[46:47], v[60:61], 0, v[80:81]
	v_lshl_add_u64 v[46:47], v[60:61], 0, v[78:79]
	v_lshl_add_u64 v[46:47], v[60:61], 0, v[76:77]
	v_lshl_add_u64 v[46:47], v[60:61], 0, v[74:75]
	v_lshl_add_u64 v[46:47], v[60:61], 0, v[72:73]
	v_lshl_add_u64 v[46:47], v[60:61], 0, v[70:71]
	v_lshl_add_u64 v[46:47], v[60:61], 0, v[68:69]
	v_lshl_add_u64 v[46:47], v[60:61], 0, v[66:67]
	v_lshl_add_u64 v[46:47], v[60:61], 0, v[64:65]
	v_lshl_add_u64 v[46:47], v[60:61], 0, v[62:63]
	v_lshl_add_u64 v[46:47], v[60:61], 0, v[58:59]
	v_lshl_add_u64 v[46:47], v[60:61], 0, v[56:57]
	global_store_dwordx2 v[60:61], v[44:45], off
	v_lshl_add_u64 v[46:47], v[60:61], 0, v[54:55]
	v_or_b32_e32 v44, 16, v128
	v_lshlrev_b32_e32 v46, 1, v44
	v_cvt_pk_bf16_f32 v44, v40, v41
	v_cvt_pk_bf16_f32 v45, v42, v43
	s_and_saveexec_b64 s[58:59], s[44:45]
	s_xor_b64 s[58:59], exec, s[58:59]
	s_cbranch_execz .LBB0_681
	v_lshlrev_b32_e32 v54, 2, v128
	v_mov_b32_e32 v55, v177
	v_lshl_add_u64 v[54:55], v[50:51], 0, v[54:55]
	v_mov_b32_e32 v47, v177
	global_store_dwordx4 v[54:55], v[40:43], off offset:64
	s_nop 1
	v_lshl_add_u64 v[40:41], v[48:49], 0, v[46:47]
	v_add_co_u32_e32 v42, vcc, 0x5100000, v40
	s_nop 1
	v_addc_co_u32_e32 v43, vcc, 0, v41, vcc
	global_store_dwordx2 v[42:43], v[44:45], off offset:256
	v_add_co_u32_e32 v42, vcc, 0x5118000, v40
	s_nop 1
	v_addc_co_u32_e32 v43, vcc, 0, v41, vcc
	v_add_co_u32_e32 v42, vcc, 0x5130000, v40
	s_nop 1
	v_addc_co_u32_e32 v43, vcc, 0, v41, vcc
	v_add_co_u32_e32 v42, vcc, 0x5148000, v40
	s_nop 1
	v_addc_co_u32_e32 v43, vcc, 0, v41, vcc
	v_add_co_u32_e32 v42, vcc, 0x5160000, v40
	s_nop 1
	v_addc_co_u32_e32 v43, vcc, 0, v41, vcc
	v_add_co_u32_e32 v42, vcc, 0x5178000, v40
	s_nop 1
	v_addc_co_u32_e32 v43, vcc, 0, v41, vcc
	v_add_co_u32_e32 v42, vcc, 0x5190000, v40
	s_nop 1
	v_addc_co_u32_e32 v43, vcc, 0, v41, vcc
	v_add_co_u32_e32 v40, vcc, 0x51a8000, v40
	s_nop 0
	v_addc_co_u32_e32 v41, vcc, 0, v41, vcc
.LBB0_681:
	s_andn2_saveexec_b64 s[58:59], s[58:59]
	s_cbranch_execz .LBB0_683
	v_mov_b32_e32 v47, v177
	v_lshl_add_u64 v[40:41], v[52:53], 0, v[46:47]
	v_add_co_u32_e32 v42, vcc, 0xb900000, v40
	s_nop 1
	v_addc_co_u32_e32 v43, vcc, 0, v41, vcc
	global_store_dwordx2 v[42:43], v[44:45], off offset:256
	v_add_co_u32_e32 v42, vcc, 0xb978000, v40
	s_nop 1
	v_addc_co_u32_e32 v43, vcc, 0, v41, vcc
	v_add_co_u32_e32 v42, vcc, 0xb9f0000, v40
	s_nop 1
	v_addc_co_u32_e32 v43, vcc, 0, v41, vcc
	v_add_co_u32_e32 v42, vcc, 0xba68000, v40
	s_nop 1
	v_addc_co_u32_e32 v43, vcc, 0, v41, vcc
	v_add_co_u32_e32 v42, vcc, 0xbae0000, v40
	s_nop 1
	v_addc_co_u32_e32 v43, vcc, 0, v41, vcc
	v_add_co_u32_e32 v42, vcc, 0xbb58000, v40
	s_nop 1
	v_addc_co_u32_e32 v43, vcc, 0, v41, vcc
	v_add_co_u32_e32 v42, vcc, 0xbbd0000, v40
	s_nop 1
	v_addc_co_u32_e32 v43, vcc, 0, v41, vcc
	v_add_co_u32_e32 v40, vcc, 0xbc48000, v40
	s_nop 0
	v_addc_co_u32_e32 v41, vcc, 0, v41, vcc
.LBB0_683:
	s_or_b64 exec, exec, s[58:59]
	v_or_b32_e32 v40, 32, v128
	v_lshlrev_b32_e32 v42, 1, v40
	v_cvt_pk_bf16_f32 v40, v36, v37
	v_cvt_pk_bf16_f32 v41, v38, v39
	s_and_saveexec_b64 s[58:59], s[44:45]
	s_xor_b64 s[58:59], exec, s[58:59]
	s_cbranch_execz .LBB0_685
	v_lshlrev_b32_e32 v44, 2, v128
	v_mov_b32_e32 v45, v177
	v_lshl_add_u64 v[44:45], v[50:51], 0, v[44:45]
	v_mov_b32_e32 v43, v177
	global_store_dwordx4 v[44:45], v[36:39], off offset:128
	s_nop 1
	v_lshl_add_u64 v[36:37], v[48:49], 0, v[42:43]
	v_add_co_u32_e32 v38, vcc, 0x5100000, v36
	s_nop 1
	v_addc_co_u32_e32 v39, vcc, 0, v37, vcc
	global_store_dwordx2 v[38:39], v[40:41], off offset:256
	v_add_co_u32_e32 v38, vcc, 0x5118000, v36
	s_nop 1
	v_addc_co_u32_e32 v39, vcc, 0, v37, vcc
	v_add_co_u32_e32 v38, vcc, 0x5130000, v36
	s_nop 1
	v_addc_co_u32_e32 v39, vcc, 0, v37, vcc
	v_add_co_u32_e32 v38, vcc, 0x5148000, v36
	s_nop 1
	v_addc_co_u32_e32 v39, vcc, 0, v37, vcc
	v_add_co_u32_e32 v38, vcc, 0x5160000, v36
	s_nop 1
	v_addc_co_u32_e32 v39, vcc, 0, v37, vcc
	v_add_co_u32_e32 v38, vcc, 0x5178000, v36
	s_nop 1
	v_addc_co_u32_e32 v39, vcc, 0, v37, vcc
	v_add_co_u32_e32 v38, vcc, 0x5190000, v36
	s_nop 1
	v_addc_co_u32_e32 v39, vcc, 0, v37, vcc
	v_add_co_u32_e32 v36, vcc, 0x51a8000, v36
	s_nop 0
	v_addc_co_u32_e32 v37, vcc, 0, v37, vcc
.LBB0_685:
	s_andn2_saveexec_b64 s[58:59], s[58:59]
	s_cbranch_execz .LBB0_687
	v_mov_b32_e32 v43, v177
	v_lshl_add_u64 v[36:37], v[52:53], 0, v[42:43]
	v_add_co_u32_e32 v38, vcc, 0xb900000, v36
	s_nop 1
	v_addc_co_u32_e32 v39, vcc, 0, v37, vcc
	global_store_dwordx2 v[38:39], v[40:41], off offset:256
	v_add_co_u32_e32 v38, vcc, 0xb978000, v36
	s_nop 1
	v_addc_co_u32_e32 v39, vcc, 0, v37, vcc
	v_add_co_u32_e32 v38, vcc, 0xb9f0000, v36
	s_nop 1
	v_addc_co_u32_e32 v39, vcc, 0, v37, vcc
	v_add_co_u32_e32 v38, vcc, 0xba68000, v36
	s_nop 1
	v_addc_co_u32_e32 v39, vcc, 0, v37, vcc
	v_add_co_u32_e32 v38, vcc, 0xbae0000, v36
	s_nop 1
	v_addc_co_u32_e32 v39, vcc, 0, v37, vcc
	v_add_co_u32_e32 v38, vcc, 0xbb58000, v36
	s_nop 1
	v_addc_co_u32_e32 v39, vcc, 0, v37, vcc
	v_add_co_u32_e32 v38, vcc, 0xbbd0000, v36
	s_nop 1
	v_addc_co_u32_e32 v39, vcc, 0, v37, vcc
	v_add_co_u32_e32 v36, vcc, 0xbc48000, v36
	s_nop 0
	v_addc_co_u32_e32 v37, vcc, 0, v37, vcc
.LBB0_687:
	s_or_b64 exec, exec, s[58:59]
	v_or_b32_e32 v36, 48, v128
	v_lshlrev_b32_e32 v38, 1, v36
	v_cvt_pk_bf16_f32 v36, v32, v33
	v_cvt_pk_bf16_f32 v37, v34, v35
	s_and_saveexec_b64 s[58:59], s[44:45]
	s_xor_b64 s[58:59], exec, s[58:59]
	s_cbranch_execz .LBB0_689
	v_lshlrev_b32_e32 v40, 2, v128
	v_mov_b32_e32 v41, v177
	v_lshl_add_u64 v[40:41], v[50:51], 0, v[40:41]
	v_mov_b32_e32 v39, v177
	global_store_dwordx4 v[40:41], v[32:35], off offset:192
	s_nop 1
	v_lshl_add_u64 v[32:33], v[48:49], 0, v[38:39]
	v_add_co_u32_e32 v34, vcc, 0x5100000, v32
	s_nop 1
	v_addc_co_u32_e32 v35, vcc, 0, v33, vcc
	global_store_dwordx2 v[34:35], v[36:37], off offset:256
	v_add_co_u32_e32 v34, vcc, 0x5118000, v32
	s_nop 1
	v_addc_co_u32_e32 v35, vcc, 0, v33, vcc
	v_add_co_u32_e32 v34, vcc, 0x5130000, v32
	s_nop 1
	v_addc_co_u32_e32 v35, vcc, 0, v33, vcc
	v_add_co_u32_e32 v34, vcc, 0x5148000, v32
	s_nop 1
	v_addc_co_u32_e32 v35, vcc, 0, v33, vcc
	v_add_co_u32_e32 v34, vcc, 0x5160000, v32
	s_nop 1
	v_addc_co_u32_e32 v35, vcc, 0, v33, vcc
	v_add_co_u32_e32 v34, vcc, 0x5178000, v32
	s_nop 1
	v_addc_co_u32_e32 v35, vcc, 0, v33, vcc
	v_add_co_u32_e32 v34, vcc, 0x5190000, v32
	s_nop 1
	v_addc_co_u32_e32 v35, vcc, 0, v33, vcc
	v_add_co_u32_e32 v32, vcc, 0x51a8000, v32
	s_nop 0
	v_addc_co_u32_e32 v33, vcc, 0, v33, vcc
.LBB0_689:
	s_andn2_saveexec_b64 s[58:59], s[58:59]
	s_cbranch_execz .LBB0_691
	v_mov_b32_e32 v39, v177
	v_lshl_add_u64 v[32:33], v[52:53], 0, v[38:39]
	v_add_co_u32_e32 v34, vcc, 0xb900000, v32
	s_nop 1
	v_addc_co_u32_e32 v35, vcc, 0, v33, vcc
	global_store_dwordx2 v[34:35], v[36:37], off offset:256
	v_add_co_u32_e32 v34, vcc, 0xb978000, v32
	s_nop 1
	v_addc_co_u32_e32 v35, vcc, 0, v33, vcc
	v_add_co_u32_e32 v34, vcc, 0xb9f0000, v32
	s_nop 1
	v_addc_co_u32_e32 v35, vcc, 0, v33, vcc
	v_add_co_u32_e32 v34, vcc, 0xba68000, v32
	s_nop 1
	v_addc_co_u32_e32 v35, vcc, 0, v33, vcc
	v_add_co_u32_e32 v34, vcc, 0xbae0000, v32
	s_nop 1
	v_addc_co_u32_e32 v35, vcc, 0, v33, vcc
	v_add_co_u32_e32 v34, vcc, 0xbb58000, v32
	s_nop 1
	v_addc_co_u32_e32 v35, vcc, 0, v33, vcc
	v_add_co_u32_e32 v34, vcc, 0xbbd0000, v32
	s_nop 1
	v_addc_co_u32_e32 v35, vcc, 0, v33, vcc
	v_add_co_u32_e32 v32, vcc, 0xbc48000, v32
	s_nop 0
	v_addc_co_u32_e32 v33, vcc, 0, v33, vcc

.LBB0_715:
	s_or_b64 exec, exec, vcc
	v_lshlrev_b32_e32 v68, 1, v128
	v_mov_b32_e32 v69, v177
	v_lshl_add_u64 v[44:45], v[44:45], 0, v[68:69]
	v_cvt_pk_bf16_f32 v28, v28, v29
	v_cvt_pk_bf16_f32 v29, v30, v31
	v_lshl_add_u64 v[30:31], v[44:45], 0, v[66:67]
	v_lshl_add_u64 v[30:31], v[44:45], 0, v[64:65]
	v_lshl_add_u64 v[30:31], v[44:45], 0, v[62:63]
	v_lshl_add_u64 v[30:31], v[44:45], 0, v[60:61]
	v_lshl_add_u64 v[30:31], v[44:45], 0, v[58:59]
	v_lshl_add_u64 v[30:31], v[44:45], 0, v[56:57]
	v_lshl_add_u64 v[30:31], v[44:45], 0, v[54:55]
	v_lshl_add_u64 v[30:31], v[44:45], 0, v[52:53]
	v_lshl_add_u64 v[30:31], v[44:45], 0, v[50:51]
	v_lshl_add_u64 v[30:31], v[44:45], 0, v[48:49]
	v_lshl_add_u64 v[30:31], v[44:45], 0, v[46:47]
	v_lshl_add_u64 v[30:31], v[44:45], 0, v[42:43]
	v_lshl_add_u64 v[30:31], v[44:45], 0, v[40:41]
	global_store_dwordx2 v[44:45], v[28:29], off
	v_lshl_add_u64 v[30:31], v[44:45], 0, v[38:39]
	v_or_b32_e32 v28, 16, v128
	v_lshlrev_b32_e32 v30, 1, v28
	v_cvt_pk_bf16_f32 v28, v24, v25
	v_cvt_pk_bf16_f32 v29, v26, v27
	s_and_saveexec_b64 s[58:59], s[44:45]
	s_xor_b64 s[58:59], exec, s[58:59]
	s_cbranch_execz .LBB0_717
	v_lshlrev_b32_e32 v38, 2, v128
	v_mov_b32_e32 v39, v177
	v_lshl_add_u64 v[38:39], v[34:35], 0, v[38:39]
	v_mov_b32_e32 v31, v177
	global_store_dwordx4 v[38:39], v[24:27], off offset:64
	s_nop 1
	v_lshl_add_u64 v[24:25], v[32:33], 0, v[30:31]
	v_add_co_u32_e32 v26, vcc, 0x5100000, v24
	s_nop 1
	v_addc_co_u32_e32 v27, vcc, 0, v25, vcc
	global_store_dwordx2 v[26:27], v[28:29], off offset:256
	v_add_co_u32_e32 v26, vcc, 0x5118000, v24
	s_nop 1
	v_addc_co_u32_e32 v27, vcc, 0, v25, vcc
	v_add_co_u32_e32 v26, vcc, 0x5130000, v24
	s_nop 1
	v_addc_co_u32_e32 v27, vcc, 0, v25, vcc
	v_add_co_u32_e32 v26, vcc, 0x5148000, v24
	s_nop 1
	v_addc_co_u32_e32 v27, vcc, 0, v25, vcc
	v_add_co_u32_e32 v26, vcc, 0x5160000, v24
	s_nop 1
	v_addc_co_u32_e32 v27, vcc, 0, v25, vcc
	v_add_co_u32_e32 v26, vcc, 0x5178000, v24
	s_nop 1
	v_addc_co_u32_e32 v27, vcc, 0, v25, vcc
	v_add_co_u32_e32 v26, vcc, 0x5190000, v24
	s_nop 1
	v_addc_co_u32_e32 v27, vcc, 0, v25, vcc
	v_add_co_u32_e32 v24, vcc, 0x51a8000, v24
	s_nop 0
	v_addc_co_u32_e32 v25, vcc, 0, v25, vcc
.LBB0_717:
	s_andn2_saveexec_b64 s[58:59], s[58:59]
	s_cbranch_execz .LBB0_719
	v_mov_b32_e32 v31, v177
	v_lshl_add_u64 v[24:25], v[36:37], 0, v[30:31]
	v_add_co_u32_e32 v26, vcc, 0xb900000, v24
	s_nop 1
	v_addc_co_u32_e32 v27, vcc, 0, v25, vcc
	global_store_dwordx2 v[26:27], v[28:29], off offset:256
	v_add_co_u32_e32 v26, vcc, 0xb978000, v24
	s_nop 1
	v_addc_co_u32_e32 v27, vcc, 0, v25, vcc
	v_add_co_u32_e32 v26, vcc, 0xb9f0000, v24
	s_nop 1
	v_addc_co_u32_e32 v27, vcc, 0, v25, vcc
	v_add_co_u32_e32 v26, vcc, 0xba68000, v24
	s_nop 1
	v_addc_co_u32_e32 v27, vcc, 0, v25, vcc
	v_add_co_u32_e32 v26, vcc, 0xbae0000, v24
	s_nop 1
	v_addc_co_u32_e32 v27, vcc, 0, v25, vcc
	v_add_co_u32_e32 v26, vcc, 0xbb58000, v24
	s_nop 1
	v_addc_co_u32_e32 v27, vcc, 0, v25, vcc
	v_add_co_u32_e32 v26, vcc, 0xbbd0000, v24
	s_nop 1
	v_addc_co_u32_e32 v27, vcc, 0, v25, vcc
	v_add_co_u32_e32 v24, vcc, 0xbc48000, v24
	s_nop 0
	v_addc_co_u32_e32 v25, vcc, 0, v25, vcc
.LBB0_719:
	s_or_b64 exec, exec, s[58:59]
	v_or_b32_e32 v24, 32, v128
	v_lshlrev_b32_e32 v26, 1, v24
	v_cvt_pk_bf16_f32 v24, v20, v21
	v_cvt_pk_bf16_f32 v25, v22, v23
	s_and_saveexec_b64 s[58:59], s[44:45]
	s_xor_b64 s[58:59], exec, s[58:59]
	s_cbranch_execz .LBB0_721
	v_lshlrev_b32_e32 v28, 2, v128
	v_mov_b32_e32 v29, v177
	v_lshl_add_u64 v[28:29], v[34:35], 0, v[28:29]
	v_mov_b32_e32 v27, v177
	global_store_dwordx4 v[28:29], v[20:23], off offset:128
	s_nop 1
	v_lshl_add_u64 v[20:21], v[32:33], 0, v[26:27]
	v_add_co_u32_e32 v22, vcc, 0x5100000, v20
	s_nop 1
	v_addc_co_u32_e32 v23, vcc, 0, v21, vcc
	global_store_dwordx2 v[22:23], v[24:25], off offset:256
	v_add_co_u32_e32 v22, vcc, 0x5118000, v20
	s_nop 1
	v_addc_co_u32_e32 v23, vcc, 0, v21, vcc
	v_add_co_u32_e32 v22, vcc, 0x5130000, v20
	s_nop 1
	v_addc_co_u32_e32 v23, vcc, 0, v21, vcc
	v_add_co_u32_e32 v22, vcc, 0x5148000, v20
	s_nop 1
	v_addc_co_u32_e32 v23, vcc, 0, v21, vcc
	v_add_co_u32_e32 v22, vcc, 0x5160000, v20
	s_nop 1
	v_addc_co_u32_e32 v23, vcc, 0, v21, vcc
	v_add_co_u32_e32 v22, vcc, 0x5178000, v20
	s_nop 1
	v_addc_co_u32_e32 v23, vcc, 0, v21, vcc
	v_add_co_u32_e32 v22, vcc, 0x5190000, v20
	s_nop 1
	v_addc_co_u32_e32 v23, vcc, 0, v21, vcc
	v_add_co_u32_e32 v20, vcc, 0x51a8000, v20
	s_nop 0
	v_addc_co_u32_e32 v21, vcc, 0, v21, vcc
.LBB0_721:
	s_andn2_saveexec_b64 s[58:59], s[58:59]
	s_cbranch_execz .LBB0_723
	v_mov_b32_e32 v27, v177
	v_lshl_add_u64 v[20:21], v[36:37], 0, v[26:27]
	v_add_co_u32_e32 v22, vcc, 0xb900000, v20
	s_nop 1
	v_addc_co_u32_e32 v23, vcc, 0, v21, vcc
	global_store_dwordx2 v[22:23], v[24:25], off offset:256
	v_add_co_u32_e32 v22, vcc, 0xb978000, v20
	s_nop 1
	v_addc_co_u32_e32 v23, vcc, 0, v21, vcc
	v_add_co_u32_e32 v22, vcc, 0xb9f0000, v20
	s_nop 1
	v_addc_co_u32_e32 v23, vcc, 0, v21, vcc
	v_add_co_u32_e32 v22, vcc, 0xba68000, v20
	s_nop 1
	v_addc_co_u32_e32 v23, vcc, 0, v21, vcc
	v_add_co_u32_e32 v22, vcc, 0xbae0000, v20
	s_nop 1
	v_addc_co_u32_e32 v23, vcc, 0, v21, vcc
	v_add_co_u32_e32 v22, vcc, 0xbb58000, v20
	s_nop 1
	v_addc_co_u32_e32 v23, vcc, 0, v21, vcc
	v_add_co_u32_e32 v22, vcc, 0xbbd0000, v20
	s_nop 1
	v_addc_co_u32_e32 v23, vcc, 0, v21, vcc
	v_add_co_u32_e32 v20, vcc, 0xbc48000, v20
	s_nop 0
	v_addc_co_u32_e32 v21, vcc, 0, v21, vcc
.LBB0_723:
	s_or_b64 exec, exec, s[58:59]
	v_or_b32_e32 v20, 48, v128
	v_lshlrev_b32_e32 v22, 1, v20
	v_cvt_pk_bf16_f32 v20, v16, v17
	v_cvt_pk_bf16_f32 v21, v18, v19
	s_and_saveexec_b64 s[58:59], s[44:45]
	s_xor_b64 s[58:59], exec, s[58:59]
	s_cbranch_execz .LBB0_725
	v_lshlrev_b32_e32 v24, 2, v128
	v_mov_b32_e32 v25, v177
	v_lshl_add_u64 v[24:25], v[34:35], 0, v[24:25]
	v_mov_b32_e32 v23, v177
	global_store_dwordx4 v[24:25], v[16:19], off offset:192
	s_nop 1
	v_lshl_add_u64 v[16:17], v[32:33], 0, v[22:23]
	v_add_co_u32_e32 v18, vcc, 0x5100000, v16
	s_nop 1
	v_addc_co_u32_e32 v19, vcc, 0, v17, vcc
	global_store_dwordx2 v[18:19], v[20:21], off offset:256
	v_add_co_u32_e32 v18, vcc, 0x5118000, v16
	s_nop 1
	v_addc_co_u32_e32 v19, vcc, 0, v17, vcc
	v_add_co_u32_e32 v18, vcc, 0x5130000, v16
	s_nop 1
	v_addc_co_u32_e32 v19, vcc, 0, v17, vcc
	v_add_co_u32_e32 v18, vcc, 0x5148000, v16
	s_nop 1
	v_addc_co_u32_e32 v19, vcc, 0, v17, vcc
	v_add_co_u32_e32 v18, vcc, 0x5160000, v16
	s_nop 1
	v_addc_co_u32_e32 v19, vcc, 0, v17, vcc
	v_add_co_u32_e32 v18, vcc, 0x5178000, v16
	s_nop 1
	v_addc_co_u32_e32 v19, vcc, 0, v17, vcc
	v_add_co_u32_e32 v18, vcc, 0x5190000, v16
	s_nop 1
	v_addc_co_u32_e32 v19, vcc, 0, v17, vcc
	v_add_co_u32_e32 v16, vcc, 0x51a8000, v16
	s_nop 0
	v_addc_co_u32_e32 v17, vcc, 0, v17, vcc
.LBB0_725:
	s_andn2_saveexec_b64 s[58:59], s[58:59]
	s_cbranch_execz .LBB0_727
	v_mov_b32_e32 v23, v177
	v_lshl_add_u64 v[16:17], v[36:37], 0, v[22:23]
	v_add_co_u32_e32 v18, vcc, 0xb900000, v16
	s_nop 1
	v_addc_co_u32_e32 v19, vcc, 0, v17, vcc
	global_store_dwordx2 v[18:19], v[20:21], off offset:256
	v_add_co_u32_e32 v18, vcc, 0xb978000, v16
	s_nop 1
	v_addc_co_u32_e32 v19, vcc, 0, v17, vcc
	v_add_co_u32_e32 v18, vcc, 0xb9f0000, v16
	s_nop 1
	v_addc_co_u32_e32 v19, vcc, 0, v17, vcc
	v_add_co_u32_e32 v18, vcc, 0xba68000, v16
	s_nop 1
	v_addc_co_u32_e32 v19, vcc, 0, v17, vcc
	v_add_co_u32_e32 v18, vcc, 0xbae0000, v16
	s_nop 1
	v_addc_co_u32_e32 v19, vcc, 0, v17, vcc
	v_add_co_u32_e32 v18, vcc, 0xbb58000, v16
	s_nop 1
	v_addc_co_u32_e32 v19, vcc, 0, v17, vcc
	v_add_co_u32_e32 v18, vcc, 0xbbd0000, v16
	s_nop 1
	v_addc_co_u32_e32 v19, vcc, 0, v17, vcc
	v_add_co_u32_e32 v16, vcc, 0xbc48000, v16
	s_nop 0
	v_addc_co_u32_e32 v17, vcc, 0, v17, vcc

.LBB0_751:
	s_or_b64 exec, exec, s[30:31]
	v_lshlrev_b32_e32 v176, 1, v128
	v_lshl_add_u64 v[30:31], v[30:31], 0, v[176:177]
	v_cvt_pk_bf16_f32 v12, v12, v13
	v_cvt_pk_bf16_f32 v13, v14, v15
	v_lshl_add_u64 v[14:15], v[30:31], 0, v[52:53]
	v_lshl_add_u64 v[14:15], v[30:31], 0, v[50:51]
	v_lshl_add_u64 v[14:15], v[30:31], 0, v[48:49]
	v_lshl_add_u64 v[14:15], v[30:31], 0, v[46:47]
	v_lshl_add_u64 v[14:15], v[30:31], 0, v[44:45]
	v_lshl_add_u64 v[14:15], v[30:31], 0, v[42:43]
	v_lshl_add_u64 v[14:15], v[30:31], 0, v[40:41]
	v_lshl_add_u64 v[14:15], v[30:31], 0, v[38:39]
	v_lshl_add_u64 v[14:15], v[30:31], 0, v[36:37]
	v_lshl_add_u64 v[14:15], v[30:31], 0, v[34:35]
	v_lshl_add_u64 v[14:15], v[30:31], 0, v[32:33]
	v_lshl_add_u64 v[14:15], v[30:31], 0, v[28:29]
	v_lshl_add_u64 v[14:15], v[30:31], 0, v[26:27]
	global_store_dwordx2 v[30:31], v[12:13], off
	v_lshl_add_u64 v[14:15], v[30:31], 0, v[24:25]
	v_or_b32_e32 v12, 16, v128
	v_lshlrev_b32_e32 v176, 1, v12
	v_cvt_pk_bf16_f32 v12, v8, v9
	v_cvt_pk_bf16_f32 v13, v10, v11
	s_and_saveexec_b64 s[30:31], s[44:45]
	s_xor_b64 s[30:31], exec, s[30:31]
	s_cbranch_execz .LBB0_753
	v_mov_b32_e32 v21, v177
	v_lshl_add_u64 v[14:15], v[18:19], 0, v[20:21]
	global_store_dwordx4 v[14:15], v[8:11], off offset:64
	s_nop 1
	v_lshl_add_u64 v[8:9], v[16:17], 0, v[176:177]
	v_add_co_u32_e32 v10, vcc, 0x5100000, v8
	s_nop 1
	v_addc_co_u32_e32 v11, vcc, 0, v9, vcc
	global_store_dwordx2 v[10:11], v[12:13], off offset:256
	v_add_co_u32_e32 v10, vcc, 0x5118000, v8
	s_nop 1
	v_addc_co_u32_e32 v11, vcc, 0, v9, vcc
	v_add_co_u32_e32 v10, vcc, 0x5130000, v8
	s_nop 1
	v_addc_co_u32_e32 v11, vcc, 0, v9, vcc
	v_add_co_u32_e32 v10, vcc, 0x5148000, v8
	s_nop 1
	v_addc_co_u32_e32 v11, vcc, 0, v9, vcc
	v_add_co_u32_e32 v10, vcc, 0x5160000, v8
	s_nop 1
	v_addc_co_u32_e32 v11, vcc, 0, v9, vcc
	v_add_co_u32_e32 v10, vcc, 0x5178000, v8
	s_nop 1
	v_addc_co_u32_e32 v11, vcc, 0, v9, vcc
	v_add_co_u32_e32 v10, vcc, 0x5190000, v8
	s_nop 1
	v_addc_co_u32_e32 v11, vcc, 0, v9, vcc
	v_add_co_u32_e32 v8, vcc, 0x51a8000, v8
	s_nop 0
	v_addc_co_u32_e32 v9, vcc, 0, v9, vcc
.LBB0_753:
	s_andn2_saveexec_b64 s[30:31], s[30:31]
	s_cbranch_execz .LBB0_755
	v_lshl_add_u64 v[8:9], v[22:23], 0, v[176:177]
	v_add_co_u32_e32 v10, vcc, 0xb900000, v8
	s_nop 1
	v_addc_co_u32_e32 v11, vcc, 0, v9, vcc
	global_store_dwordx2 v[10:11], v[12:13], off offset:256
	v_add_co_u32_e32 v10, vcc, 0xb978000, v8
	s_nop 1
	v_addc_co_u32_e32 v11, vcc, 0, v9, vcc
	v_add_co_u32_e32 v10, vcc, 0xb9f0000, v8
	s_nop 1
	v_addc_co_u32_e32 v11, vcc, 0, v9, vcc
	v_add_co_u32_e32 v10, vcc, 0xba68000, v8
	s_nop 1
	v_addc_co_u32_e32 v11, vcc, 0, v9, vcc
	v_add_co_u32_e32 v10, vcc, 0xbae0000, v8
	s_nop 1
	v_addc_co_u32_e32 v11, vcc, 0, v9, vcc
	v_add_co_u32_e32 v10, vcc, 0xbb58000, v8
	s_nop 1
	v_addc_co_u32_e32 v11, vcc, 0, v9, vcc
	v_add_co_u32_e32 v10, vcc, 0xbbd0000, v8
	s_nop 1
	v_addc_co_u32_e32 v11, vcc, 0, v9, vcc
	v_add_co_u32_e32 v8, vcc, 0xbc48000, v8
	s_nop 0
	v_addc_co_u32_e32 v9, vcc, 0, v9, vcc
.LBB0_755:
	s_or_b64 exec, exec, s[30:31]
	v_or_b32_e32 v8, 32, v128
	v_lshlrev_b32_e32 v176, 1, v8
	v_cvt_pk_bf16_f32 v8, v4, v5
	v_cvt_pk_bf16_f32 v9, v6, v7
	s_and_saveexec_b64 s[30:31], s[44:45]
	s_xor_b64 s[30:31], exec, s[30:31]
	s_cbranch_execz .LBB0_757
	v_mov_b32_e32 v21, v177
	v_lshl_add_u64 v[10:11], v[18:19], 0, v[20:21]
	global_store_dwordx4 v[10:11], v[4:7], off offset:128
	s_nop 1
	v_lshl_add_u64 v[4:5], v[16:17], 0, v[176:177]
	v_add_co_u32_e32 v6, vcc, 0x5100000, v4
	s_nop 1
	v_addc_co_u32_e32 v7, vcc, 0, v5, vcc
	global_store_dwordx2 v[6:7], v[8:9], off offset:256
	v_add_co_u32_e32 v6, vcc, 0x5118000, v4
	s_nop 1
	v_addc_co_u32_e32 v7, vcc, 0, v5, vcc
	v_add_co_u32_e32 v6, vcc, 0x5130000, v4
	s_nop 1
	v_addc_co_u32_e32 v7, vcc, 0, v5, vcc
	v_add_co_u32_e32 v6, vcc, 0x5148000, v4
	s_nop 1
	v_addc_co_u32_e32 v7, vcc, 0, v5, vcc
	v_add_co_u32_e32 v6, vcc, 0x5160000, v4
	s_nop 1
	v_addc_co_u32_e32 v7, vcc, 0, v5, vcc
	v_add_co_u32_e32 v6, vcc, 0x5178000, v4
	s_nop 1
	v_addc_co_u32_e32 v7, vcc, 0, v5, vcc
	v_add_co_u32_e32 v6, vcc, 0x5190000, v4
	s_nop 1
	v_addc_co_u32_e32 v7, vcc, 0, v5, vcc
	v_add_co_u32_e32 v4, vcc, 0x51a8000, v4
	s_nop 0
	v_addc_co_u32_e32 v5, vcc, 0, v5, vcc
.LBB0_757:
	s_andn2_saveexec_b64 s[30:31], s[30:31]
	s_cbranch_execz .LBB0_759
	v_lshl_add_u64 v[4:5], v[22:23], 0, v[176:177]
	v_add_co_u32_e32 v6, vcc, 0xb900000, v4
	s_nop 1
	v_addc_co_u32_e32 v7, vcc, 0, v5, vcc
	global_store_dwordx2 v[6:7], v[8:9], off offset:256
	v_add_co_u32_e32 v6, vcc, 0xb978000, v4
	s_nop 1
	v_addc_co_u32_e32 v7, vcc, 0, v5, vcc
	v_add_co_u32_e32 v6, vcc, 0xb9f0000, v4
	s_nop 1
	v_addc_co_u32_e32 v7, vcc, 0, v5, vcc
	v_add_co_u32_e32 v6, vcc, 0xba68000, v4
	s_nop 1
	v_addc_co_u32_e32 v7, vcc, 0, v5, vcc
	v_add_co_u32_e32 v6, vcc, 0xbae0000, v4
	s_nop 1
	v_addc_co_u32_e32 v7, vcc, 0, v5, vcc
	v_add_co_u32_e32 v6, vcc, 0xbb58000, v4
	s_nop 1
	v_addc_co_u32_e32 v7, vcc, 0, v5, vcc
	v_add_co_u32_e32 v6, vcc, 0xbbd0000, v4
	s_nop 1
	v_addc_co_u32_e32 v7, vcc, 0, v5, vcc
	v_add_co_u32_e32 v4, vcc, 0xbc48000, v4
	s_nop 0
	v_addc_co_u32_e32 v5, vcc, 0, v5, vcc
.LBB0_759:
	s_or_b64 exec, exec, s[30:31]
	v_or_b32_e32 v4, 48, v128
	v_lshlrev_b32_e32 v176, 1, v4
	v_cvt_pk_bf16_f32 v4, v0, v1
	v_cvt_pk_bf16_f32 v5, v2, v3
	s_and_saveexec_b64 s[30:31], s[44:45]
	s_xor_b64 s[30:31], exec, s[30:31]
	s_cbranch_execz .LBB0_761
	v_mov_b32_e32 v21, v177
	v_lshl_add_u64 v[6:7], v[18:19], 0, v[20:21]
	global_store_dwordx4 v[6:7], v[0:3], off offset:192
	s_nop 1
	v_lshl_add_u64 v[0:1], v[16:17], 0, v[176:177]
	v_add_co_u32_e32 v2, vcc, 0x5100000, v0
	s_nop 1
	v_addc_co_u32_e32 v3, vcc, 0, v1, vcc
	global_store_dwordx2 v[2:3], v[4:5], off offset:256
	v_add_co_u32_e32 v2, vcc, 0x5118000, v0
	s_nop 1
	v_addc_co_u32_e32 v3, vcc, 0, v1, vcc
	v_add_co_u32_e32 v2, vcc, 0x5130000, v0
	s_nop 1
	v_addc_co_u32_e32 v3, vcc, 0, v1, vcc
	v_add_co_u32_e32 v2, vcc, 0x5148000, v0
	s_nop 1
	v_addc_co_u32_e32 v3, vcc, 0, v1, vcc
	v_add_co_u32_e32 v2, vcc, 0x5160000, v0
	s_nop 1
	v_addc_co_u32_e32 v3, vcc, 0, v1, vcc
	v_add_co_u32_e32 v2, vcc, 0x5178000, v0
	s_nop 1
	v_addc_co_u32_e32 v3, vcc, 0, v1, vcc
	v_add_co_u32_e32 v2, vcc, 0x5190000, v0
	s_nop 1
	v_addc_co_u32_e32 v3, vcc, 0, v1, vcc
	v_add_co_u32_e32 v0, vcc, 0x51a8000, v0
	s_nop 0
	v_addc_co_u32_e32 v1, vcc, 0, v1, vcc
.LBB0_761:
	s_andn2_saveexec_b64 s[30:31], s[30:31]
	s_cbranch_execz .LBB0_763
	v_lshl_add_u64 v[0:1], v[22:23], 0, v[176:177]
	v_add_co_u32_e32 v2, vcc, 0xb900000, v0
	s_nop 1
	v_addc_co_u32_e32 v3, vcc, 0, v1, vcc
	global_store_dwordx2 v[2:3], v[4:5], off offset:256
	v_add_co_u32_e32 v2, vcc, 0xb978000, v0
	s_nop 1
	v_addc_co_u32_e32 v3, vcc, 0, v1, vcc
	v_add_co_u32_e32 v2, vcc, 0xb9f0000, v0
	s_nop 1
	v_addc_co_u32_e32 v3, vcc, 0, v1, vcc
	v_add_co_u32_e32 v2, vcc, 0xba68000, v0
	s_nop 1
	v_addc_co_u32_e32 v3, vcc, 0, v1, vcc
	v_add_co_u32_e32 v2, vcc, 0xbae0000, v0
	s_nop 1
	v_addc_co_u32_e32 v3, vcc, 0, v1, vcc
	v_add_co_u32_e32 v2, vcc, 0xbb58000, v0
	s_nop 1
	v_addc_co_u32_e32 v3, vcc, 0, v1, vcc
	v_add_co_u32_e32 v2, vcc, 0xbbd0000, v0
	s_nop 1
	v_addc_co_u32_e32 v3, vcc, 0, v1, vcc
	v_add_co_u32_e32 v0, vcc, 0xbc48000, v0
	s_nop 0
	v_addc_co_u32_e32 v1, vcc, 0, v1, vcc
